# ssd_pass2 M section: the 16 A-cumsum LDS values read once in front of the section instead of one waited LDS read inside each of the 32 exec-masked element blocks
# speedup vs baseline: 1.0065x; 1.0012x over previous
; __device__ __forceinline__ bf f2bf(float f) { return (bf)(pk2(f, 0.f) & 0xFFFFu); }
; __device__ __forceinline__ void ssd_pass2(const Params& p, int layer, int task, char* sm) {
;     ...
;     {
;       const float* pv = p.ST + (((size_t)(b * 128 + c) * 16 + hd) * 64 + 32 * wc2 + r32) * 128 + 8 * h5;
; #pragma unroll
;       for (int ks = 0; ks < 8; ks++) {
;         float4 u0 = *(const float4*)(pv + ks * 16), u1 = *(const float4*)(pv + ks * 16 + 4);
;         unsigned q0 = pk2(u0.x, u0.y), q1 = pk2(u0.z, u0.w), q2 = pk2(u1.x, u1.y), q3 = pk2(u1.z, u1.w);
;         pfr[ks][0] = (short)(q0 & 0xFFFF); pfr[ks][1] = (short)(q0 >> 16); pfr[ks][2] = (short)(q1 & 0xFFFF); pfr[ks][3] = (short)(q1 >> 16);
;         pfr[ks][4] = (short)(q2 & 0xFFFF); pfr[ks][5] = (short)(q2 >> 16); pfr[ks][6] = (short)(q3 & 0xFFFF); pfr[ks][7] = (short)(q3 >> 16);
;       }
;     }
;     {
;       const float dsk = p.ssd_d[layer * 16 + hd];
; #pragma unroll
;       for (int j = 0; j < 2; j++) {
;         const int s = 64 * wc + 32 * j + r32;
;         if (s < nS) {
;           const float as = sAcs[s * 8 + hh];
; #pragma unroll
;           for (int r = 0; r < 16; r++) {
;             const int lp = 32 * wr + 8 * (r >> 2) + 4 * h5 + (r & 3); const int l = 64 * lh + lp;
;             float v = 0.f;
;             if (s <= l) v = cb[j][r] * __expf(sAcs[l * 8 + hh] - as);
;             if (s == l) v += dsk * __builtin_amdgcn_rcpf(sDt[l * 8 + hh]);
;             sM[lp * 136 + s] = f2bf(v);
.LBB0_1625:
	s_or_b32 s74, s78, s79
	s_lshl_b32 s68, s74, 6
	v_lshl_add_u64 v[16:17], v[112:113], 0, s[68:69]
	v_lshlrev_b64 v[16:17], 9, v[16:17]
	v_lshl_add_u64 v[16:17], v[114:115], 0, v[16:17]
	global_load_dwordx4 v[100:103], v[16:17], off offset:16
	global_load_dwordx4 v[108:111], v[16:17], off
	global_load_dwordx4 v[92:95], v[16:17], off offset:80
	global_load_dwordx4 v[104:107], v[16:17], off offset:64
	global_load_dwordx4 v[84:87], v[16:17], off offset:144
	global_load_dwordx4 v[96:99], v[16:17], off offset:128
	global_load_dwordx4 v[76:79], v[16:17], off offset:208
	global_load_dwordx4 v[88:91], v[16:17], off offset:192
	global_load_dwordx4 v[68:71], v[16:17], off offset:272
	global_load_dwordx4 v[80:83], v[16:17], off offset:256
	global_load_dwordx4 v[60:63], v[16:17], off offset:336
	global_load_dwordx4 v[72:75], v[16:17], off offset:320
	global_load_dwordx4 v[52:55], v[16:17], off offset:400
	global_load_dwordx4 v[64:67], v[16:17], off offset:384
	global_load_dwordx4 v[48:51], v[16:17], off offset:464
	global_load_dwordx4 v[56:59], v[16:17], off offset:448
	v_readlane_b32 s52, v254, 26
	s_or_b32 s74, s74, s52
	s_mov_b32 s75, s69
	v_readlane_b32 s52, v252, 32
	s_lshl_b64 s[74:75], s[74:75], 2
	v_readlane_b32 s58, v252, 38
	v_readlane_b32 s59, v252, 39
	s_add_u32 s74, s58, s74
	s_addc_u32 s75, s59, s75
	global_load_dword v16, v145, s[74:75]
	v_readlane_b32 s53, v252, 33
	v_readlane_b32 s54, v252, 34
	v_readlane_b32 s55, v252, 35
	v_readlane_b32 s56, v252, 36
	v_readlane_b32 s57, v252, 37
	v_readlane_b32 s60, v252, 40
	v_readlane_b32 s61, v252, 41
	v_readlane_b32 s62, v252, 42
	v_readlane_b32 s63, v252, 43
	v_readlane_b32 s64, v252, 44
	v_readlane_b32 s65, v252, 45
	v_readlane_b32 s66, v252, 46
	v_readlane_b32 s67, v252, 47
	v_lshl_add_u32 v21, s78, 2, v229
	v_lshl_add_u32 v22, s78, 2, v230
	v_lshl_add_u32 v23, s78, 2, v231
	v_lshl_add_u32 v24, s78, 2, v232
	v_lshl_add_u32 v25, s78, 2, v233
	v_lshl_add_u32 v26, s78, 2, v234
	v_lshl_add_u32 v27, s78, 2, v235
	v_lshl_add_u32 v28, s78, 2, v236
	v_lshl_add_u32 v29, s78, 2, v237
	v_lshl_add_u32 v30, s78, 2, v238
	v_lshl_add_u32 v31, s78, 2, v239
	v_lshl_add_u32 v32, s78, 2, v240
	v_lshl_add_u32 v33, s78, 2, v241
	v_lshl_add_u32 v34, s78, 2, v242
	v_lshl_add_u32 v35, s78, 2, v243
	v_lshl_add_u32 v36, s78, 2, v244
	ds_read_b32 v21, v21
	ds_read_b32 v22, v22
	ds_read_b32 v23, v23
	ds_read_b32 v24, v24
	ds_read_b32 v25, v25
	ds_read_b32 v26, v26
	ds_read_b32 v27, v27
	ds_read_b32 v28, v28
	ds_read_b32 v29, v29
	ds_read_b32 v30, v30
	ds_read_b32 v31, v31
	ds_read_b32 v32, v32
	ds_read_b32 v33, v33
	ds_read_b32 v34, v34
	ds_read_b32 v35, v35
	ds_read_b32 v36, v36
	s_waitcnt lgkmcnt(0)
	s_and_saveexec_b64 vcc, s[6:7]
	s_cbranch_execz .LBB0_1691
	v_add_u32_e32 v17, s78, v189
	v_lshl_add_u32 v17, v17, 2, s84
	ds_read_b32 v18, v17
	s_waitcnt lgkmcnt(0)
	v_readlane_b32 s52, v254, 48
	v_mov_b32_e32 v19, 0
	v_readlane_b32 s53, v254, 49
	s_and_saveexec_b64 s[74:75], s[52:53]
	s_cbranch_execz .LBB0_1628
	v_sub_f32_e32 v19, v21, v18
	v_mul_f32_e32 v19, 0x3fb8aa3b, v19
	v_exp_f32_e32 v19, v19
	s_nop 0
	v_mul_f32_e32 v19, v0, v19

; __device__ __forceinline__ bf f2bf(float f) { return (bf)(pk2(f, 0.f) & 0xFFFFu); }
; __device__ __forceinline__ void ssd_pass2(const Params& p, int layer, int task, char* sm) {
;     ...
;           for (int r = 0; r < 16; r++) {
;             const int lp = 32 * wr + 8 * (r >> 2) + 4 * h5 + (r & 3); const int l = 64 * lh + lp;
;             float v = 0.f;
;             if (s <= l) v = cb[j][r] * __expf(sAcs[l * 8 + hh] - as);
;             if (s == l) v += dsk * __builtin_amdgcn_rcpf(sDt[l * 8 + hh]);
;             sM[lp * 136 + s] = f2bf(v);
.LBB0_1630:
	s_or_b64 exec, exec, s[74:75]
	v_cvt_pk_bf16_f32 v19, v19, s0
	v_readlane_b32 s52, v254, 52
	ds_write_b16 v190, v19 offset:25600
	v_mov_b32_e32 v19, 0
	v_readlane_b32 s53, v254, 53
	s_and_saveexec_b64 s[74:75], s[52:53]
	s_cbranch_execz .LBB0_1632
	v_sub_f32_e32 v19, v22, v18
	v_mul_f32_e32 v19, 0x3fb8aa3b, v19
	v_exp_f32_e32 v19, v19
	s_nop 0
	v_mul_f32_e32 v19, v1, v19

; __device__ __forceinline__ bf f2bf(float f) { return (bf)(pk2(f, 0.f) & 0xFFFFu); }
; __device__ __forceinline__ void ssd_pass2(const Params& p, int layer, int task, char* sm) {
;     ...
;           for (int r = 0; r < 16; r++) {
;             const int lp = 32 * wr + 8 * (r >> 2) + 4 * h5 + (r & 3); const int l = 64 * lh + lp;
;             float v = 0.f;
;             if (s <= l) v = cb[j][r] * __expf(sAcs[l * 8 + hh] - as);
;             if (s == l) v += dsk * __builtin_amdgcn_rcpf(sDt[l * 8 + hh]);
;             sM[lp * 136 + s] = f2bf(v);
.LBB0_1634:
	s_or_b64 exec, exec, s[74:75]
	v_cvt_pk_bf16_f32 v19, v19, s0
	v_readlane_b32 s52, v254, 56
	ds_write_b16 v191, v19 offset:25600
	v_mov_b32_e32 v19, 0
	v_readlane_b32 s53, v254, 57
	s_and_saveexec_b64 s[74:75], s[52:53]
	s_cbranch_execz .LBB0_1636
	v_sub_f32_e32 v19, v23, v18
	v_mul_f32_e32 v19, 0x3fb8aa3b, v19
	v_exp_f32_e32 v19, v19
	s_nop 0
	v_mul_f32_e32 v19, v2, v19

; __device__ __forceinline__ bf f2bf(float f) { return (bf)(pk2(f, 0.f) & 0xFFFFu); }
; __device__ __forceinline__ void ssd_pass2(const Params& p, int layer, int task, char* sm) {
;     ...
;           for (int r = 0; r < 16; r++) {
;             const int lp = 32 * wr + 8 * (r >> 2) + 4 * h5 + (r & 3); const int l = 64 * lh + lp;
;             float v = 0.f;
;             if (s <= l) v = cb[j][r] * __expf(sAcs[l * 8 + hh] - as);
;             if (s == l) v += dsk * __builtin_amdgcn_rcpf(sDt[l * 8 + hh]);
;             sM[lp * 136 + s] = f2bf(v);
.LBB0_1638:
	s_or_b64 exec, exec, s[74:75]
	v_cvt_pk_bf16_f32 v19, v19, s0
	v_readlane_b32 s52, v254, 60
	ds_write_b16 v192, v19 offset:25600
	v_mov_b32_e32 v19, 0
	v_readlane_b32 s53, v254, 61
	s_and_saveexec_b64 s[74:75], s[52:53]
	s_cbranch_execz .LBB0_1640
	v_sub_f32_e32 v19, v24, v18
	v_mul_f32_e32 v19, 0x3fb8aa3b, v19
	v_exp_f32_e32 v19, v19
	s_nop 0
	v_mul_f32_e32 v19, v3, v19

; __device__ __forceinline__ bf f2bf(float f) { return (bf)(pk2(f, 0.f) & 0xFFFFu); }
; __device__ __forceinline__ void ssd_pass2(const Params& p, int layer, int task, char* sm) {
;     ...
;           for (int r = 0; r < 16; r++) {
;             const int lp = 32 * wr + 8 * (r >> 2) + 4 * h5 + (r & 3); const int l = 64 * lh + lp;
;             float v = 0.f;
;             if (s <= l) v = cb[j][r] * __expf(sAcs[l * 8 + hh] - as);
;             if (s == l) v += dsk * __builtin_amdgcn_rcpf(sDt[l * 8 + hh]);
;             sM[lp * 136 + s] = f2bf(v);
.LBB0_1642:
	s_or_b64 exec, exec, s[74:75]
	v_cvt_pk_bf16_f32 v19, v19, s0
	v_readlane_b32 s52, v255, 1
	ds_write_b16 v193, v19 offset:25600
	v_mov_b32_e32 v19, 0
	v_readlane_b32 s53, v255, 2
	s_and_saveexec_b64 s[74:75], s[52:53]
	s_cbranch_execz .LBB0_1644
	v_sub_f32_e32 v19, v25, v18
	v_mul_f32_e32 v19, 0x3fb8aa3b, v19
	v_exp_f32_e32 v19, v19
	s_nop 0
	v_mul_f32_e32 v19, v4, v19

; __device__ __forceinline__ bf f2bf(float f) { return (bf)(pk2(f, 0.f) & 0xFFFFu); }
; __device__ __forceinline__ void ssd_pass2(const Params& p, int layer, int task, char* sm) {
;     ...
;           for (int r = 0; r < 16; r++) {
;             const int lp = 32 * wr + 8 * (r >> 2) + 4 * h5 + (r & 3); const int l = 64 * lh + lp;
;             float v = 0.f;
;             if (s <= l) v = cb[j][r] * __expf(sAcs[l * 8 + hh] - as);
;             if (s == l) v += dsk * __builtin_amdgcn_rcpf(sDt[l * 8 + hh]);
;             sM[lp * 136 + s] = f2bf(v);
.LBB0_1646:
	s_or_b64 exec, exec, s[74:75]
	v_cvt_pk_bf16_f32 v19, v19, s0
	v_readlane_b32 s52, v255, 5
	ds_write_b16 v194, v19 offset:25600
	v_mov_b32_e32 v19, 0
	v_readlane_b32 s53, v255, 6
	s_and_saveexec_b64 s[74:75], s[52:53]
	s_cbranch_execz .LBB0_1648
	v_sub_f32_e32 v19, v26, v18
	v_mul_f32_e32 v19, 0x3fb8aa3b, v19
	v_exp_f32_e32 v19, v19
	s_nop 0
	v_mul_f32_e32 v19, v5, v19

; __device__ __forceinline__ bf f2bf(float f) { return (bf)(pk2(f, 0.f) & 0xFFFFu); }
; __device__ __forceinline__ void ssd_pass2(const Params& p, int layer, int task, char* sm) {
;     ...
;           for (int r = 0; r < 16; r++) {
;             const int lp = 32 * wr + 8 * (r >> 2) + 4 * h5 + (r & 3); const int l = 64 * lh + lp;
;             float v = 0.f;
;             if (s <= l) v = cb[j][r] * __expf(sAcs[l * 8 + hh] - as);
;             if (s == l) v += dsk * __builtin_amdgcn_rcpf(sDt[l * 8 + hh]);
;             sM[lp * 136 + s] = f2bf(v);
.LBB0_1650:
	s_or_b64 exec, exec, s[74:75]
	v_cvt_pk_bf16_f32 v19, v19, s0
	v_readlane_b32 s52, v255, 9
	ds_write_b16 v195, v19 offset:25600
	v_mov_b32_e32 v19, 0
	v_readlane_b32 s53, v255, 10
	s_and_saveexec_b64 s[74:75], s[52:53]
	s_cbranch_execz .LBB0_1652
	v_sub_f32_e32 v19, v27, v18
	v_mul_f32_e32 v19, 0x3fb8aa3b, v19
	v_exp_f32_e32 v19, v19
	s_nop 0
	v_mul_f32_e32 v19, v6, v19

; __device__ __forceinline__ bf f2bf(float f) { return (bf)(pk2(f, 0.f) & 0xFFFFu); }
; __device__ __forceinline__ void ssd_pass2(const Params& p, int layer, int task, char* sm) {
;     ...
;           for (int r = 0; r < 16; r++) {
;             const int lp = 32 * wr + 8 * (r >> 2) + 4 * h5 + (r & 3); const int l = 64 * lh + lp;
;             float v = 0.f;
;             if (s <= l) v = cb[j][r] * __expf(sAcs[l * 8 + hh] - as);
;             if (s == l) v += dsk * __builtin_amdgcn_rcpf(sDt[l * 8 + hh]);
;             sM[lp * 136 + s] = f2bf(v);
.LBB0_1654:
	s_or_b64 exec, exec, s[74:75]
	v_cvt_pk_bf16_f32 v19, v19, s0
	v_readlane_b32 s52, v255, 13
	ds_write_b16 v196, v19 offset:25600
	v_mov_b32_e32 v19, 0
	v_readlane_b32 s53, v255, 14
	s_and_saveexec_b64 s[74:75], s[52:53]
	s_cbranch_execz .LBB0_1656
	v_sub_f32_e32 v19, v28, v18
	v_mul_f32_e32 v19, 0x3fb8aa3b, v19
	v_exp_f32_e32 v19, v19
	s_nop 0
	v_mul_f32_e32 v19, v7, v19

; __device__ __forceinline__ bf f2bf(float f) { return (bf)(pk2(f, 0.f) & 0xFFFFu); }
; __device__ __forceinline__ void ssd_pass2(const Params& p, int layer, int task, char* sm) {
;     ...
;           for (int r = 0; r < 16; r++) {
;             const int lp = 32 * wr + 8 * (r >> 2) + 4 * h5 + (r & 3); const int l = 64 * lh + lp;
;             float v = 0.f;
;             if (s <= l) v = cb[j][r] * __expf(sAcs[l * 8 + hh] - as);
;             if (s == l) v += dsk * __builtin_amdgcn_rcpf(sDt[l * 8 + hh]);
;             sM[lp * 136 + s] = f2bf(v);
.LBB0_1658:
	s_or_b64 exec, exec, s[74:75]
	v_cvt_pk_bf16_f32 v19, v19, s0
	v_readlane_b32 s52, v255, 17
	ds_write_b16 v197, v19 offset:25600
	v_mov_b32_e32 v19, 0
	v_readlane_b32 s53, v255, 18
	s_and_saveexec_b64 s[74:75], s[52:53]
	s_cbranch_execz .LBB0_1660
	v_sub_f32_e32 v19, v29, v18
	v_mul_f32_e32 v19, 0x3fb8aa3b, v19
	v_exp_f32_e32 v19, v19
	s_nop 0
	v_mul_f32_e32 v19, v8, v19

; __device__ __forceinline__ bf f2bf(float f) { return (bf)(pk2(f, 0.f) & 0xFFFFu); }
; __device__ __forceinline__ void ssd_pass2(const Params& p, int layer, int task, char* sm) {
;     ...
;           for (int r = 0; r < 16; r++) {
;             const int lp = 32 * wr + 8 * (r >> 2) + 4 * h5 + (r & 3); const int l = 64 * lh + lp;
;             float v = 0.f;
;             if (s <= l) v = cb[j][r] * __expf(sAcs[l * 8 + hh] - as);
;             if (s == l) v += dsk * __builtin_amdgcn_rcpf(sDt[l * 8 + hh]);
;             sM[lp * 136 + s] = f2bf(v);
.LBB0_1662:
	s_or_b64 exec, exec, s[74:75]
	v_cvt_pk_bf16_f32 v19, v19, s0
	v_readlane_b32 s52, v255, 21
	ds_write_b16 v213, v19 offset:25600
	v_mov_b32_e32 v19, 0
	v_readlane_b32 s53, v255, 22
	s_and_saveexec_b64 s[74:75], s[52:53]
	s_cbranch_execz .LBB0_1664
	v_sub_f32_e32 v19, v30, v18
	v_mul_f32_e32 v19, 0x3fb8aa3b, v19
	v_exp_f32_e32 v19, v19
	s_nop 0
	v_mul_f32_e32 v19, v9, v19

; __device__ __forceinline__ bf f2bf(float f) { return (bf)(pk2(f, 0.f) & 0xFFFFu); }
; __device__ __forceinline__ void ssd_pass2(const Params& p, int layer, int task, char* sm) {
;     ...
;           for (int r = 0; r < 16; r++) {
;             const int lp = 32 * wr + 8 * (r >> 2) + 4 * h5 + (r & 3); const int l = 64 * lh + lp;
;             float v = 0.f;
;             if (s <= l) v = cb[j][r] * __expf(sAcs[l * 8 + hh] - as);
;             if (s == l) v += dsk * __builtin_amdgcn_rcpf(sDt[l * 8 + hh]);
;             sM[lp * 136 + s] = f2bf(v);
.LBB0_1666:
	s_or_b64 exec, exec, s[74:75]
	v_cvt_pk_bf16_f32 v19, v19, s0
	v_readlane_b32 s52, v255, 25
	ds_write_b16 v214, v19 offset:25600
	v_mov_b32_e32 v19, 0
	v_readlane_b32 s53, v255, 26
	s_and_saveexec_b64 s[74:75], s[52:53]
	s_cbranch_execz .LBB0_1668
	v_sub_f32_e32 v19, v31, v18
	v_mul_f32_e32 v19, 0x3fb8aa3b, v19
	v_exp_f32_e32 v19, v19
	s_nop 0
	v_mul_f32_e32 v19, v10, v19

; __device__ __forceinline__ bf f2bf(float f) { return (bf)(pk2(f, 0.f) & 0xFFFFu); }
; __device__ __forceinline__ void ssd_pass2(const Params& p, int layer, int task, char* sm) {
;     ...
;           for (int r = 0; r < 16; r++) {
;             const int lp = 32 * wr + 8 * (r >> 2) + 4 * h5 + (r & 3); const int l = 64 * lh + lp;
;             float v = 0.f;
;             if (s <= l) v = cb[j][r] * __expf(sAcs[l * 8 + hh] - as);
;             if (s == l) v += dsk * __builtin_amdgcn_rcpf(sDt[l * 8 + hh]);
;             sM[lp * 136 + s] = f2bf(v);
.LBB0_1670:
	s_or_b64 exec, exec, s[74:75]
	v_cvt_pk_bf16_f32 v19, v19, s0
	v_readlane_b32 s52, v255, 29
	ds_write_b16 v215, v19 offset:25600
	v_mov_b32_e32 v19, 0
	v_readlane_b32 s53, v255, 30
	s_and_saveexec_b64 s[74:75], s[52:53]
	s_cbranch_execz .LBB0_1672
	v_sub_f32_e32 v19, v32, v18
	v_mul_f32_e32 v19, 0x3fb8aa3b, v19
	v_exp_f32_e32 v19, v19
	s_nop 0
	v_mul_f32_e32 v19, v11, v19

; __device__ __forceinline__ bf f2bf(float f) { return (bf)(pk2(f, 0.f) & 0xFFFFu); }
; __device__ __forceinline__ void ssd_pass2(const Params& p, int layer, int task, char* sm) {
;     ...
;           for (int r = 0; r < 16; r++) {
;             const int lp = 32 * wr + 8 * (r >> 2) + 4 * h5 + (r & 3); const int l = 64 * lh + lp;
;             float v = 0.f;
;             if (s <= l) v = cb[j][r] * __expf(sAcs[l * 8 + hh] - as);
;             if (s == l) v += dsk * __builtin_amdgcn_rcpf(sDt[l * 8 + hh]);
;             sM[lp * 136 + s] = f2bf(v);
.LBB0_1674:
	s_or_b64 exec, exec, s[74:75]
	v_cvt_pk_bf16_f32 v19, v19, s0
	v_readlane_b32 s52, v255, 33
	ds_write_b16 v216, v19 offset:25600
	v_mov_b32_e32 v19, 0
	v_readlane_b32 s53, v255, 34
	s_and_saveexec_b64 s[74:75], s[52:53]
	s_cbranch_execz .LBB0_1676
	v_sub_f32_e32 v19, v33, v18
	v_mul_f32_e32 v19, 0x3fb8aa3b, v19
	v_exp_f32_e32 v19, v19
	s_nop 0
	v_mul_f32_e32 v19, v12, v19

; __device__ __forceinline__ bf f2bf(float f) { return (bf)(pk2(f, 0.f) & 0xFFFFu); }
; __device__ __forceinline__ void ssd_pass2(const Params& p, int layer, int task, char* sm) {
;     ...
;           for (int r = 0; r < 16; r++) {
;             const int lp = 32 * wr + 8 * (r >> 2) + 4 * h5 + (r & 3); const int l = 64 * lh + lp;
;             float v = 0.f;
;             if (s <= l) v = cb[j][r] * __expf(sAcs[l * 8 + hh] - as);
;             if (s == l) v += dsk * __builtin_amdgcn_rcpf(sDt[l * 8 + hh]);
;             sM[lp * 136 + s] = f2bf(v);
.LBB0_1678:
	s_or_b64 exec, exec, s[74:75]
	v_cvt_pk_bf16_f32 v19, v19, s0
	v_readlane_b32 s52, v255, 37
	ds_write_b16 v217, v19 offset:25600
	v_mov_b32_e32 v19, 0
	v_readlane_b32 s53, v255, 38
	s_and_saveexec_b64 s[74:75], s[52:53]
	s_cbranch_execz .LBB0_1680
	v_sub_f32_e32 v19, v34, v18
	v_mul_f32_e32 v19, 0x3fb8aa3b, v19
	v_exp_f32_e32 v19, v19
	s_nop 0
	v_mul_f32_e32 v19, v13, v19

; __device__ __forceinline__ bf f2bf(float f) { return (bf)(pk2(f, 0.f) & 0xFFFFu); }
; __device__ __forceinline__ void ssd_pass2(const Params& p, int layer, int task, char* sm) {
;     ...
;           for (int r = 0; r < 16; r++) {
;             const int lp = 32 * wr + 8 * (r >> 2) + 4 * h5 + (r & 3); const int l = 64 * lh + lp;
;             float v = 0.f;
;             if (s <= l) v = cb[j][r] * __expf(sAcs[l * 8 + hh] - as);
;             if (s == l) v += dsk * __builtin_amdgcn_rcpf(sDt[l * 8 + hh]);
;             sM[lp * 136 + s] = f2bf(v);
.LBB0_1682:
	s_or_b64 exec, exec, s[74:75]
	v_cvt_pk_bf16_f32 v19, v19, s0
	v_readlane_b32 s52, v255, 41
	ds_write_b16 v218, v19 offset:25600
	v_mov_b32_e32 v19, 0
	v_readlane_b32 s53, v255, 42
	s_and_saveexec_b64 s[74:75], s[52:53]
	s_cbranch_execz .LBB0_1684
	v_sub_f32_e32 v19, v35, v18
	v_mul_f32_e32 v19, 0x3fb8aa3b, v19
	v_exp_f32_e32 v19, v19
	s_nop 0
	v_mul_f32_e32 v19, v14, v19

; __device__ __forceinline__ bf f2bf(float f) { return (bf)(pk2(f, 0.f) & 0xFFFFu); }
; __device__ __forceinline__ void ssd_pass2(const Params& p, int layer, int task, char* sm) {
;     ...
;           for (int r = 0; r < 16; r++) {
;             const int lp = 32 * wr + 8 * (r >> 2) + 4 * h5 + (r & 3); const int l = 64 * lh + lp;
;             float v = 0.f;
;             if (s <= l) v = cb[j][r] * __expf(sAcs[l * 8 + hh] - as);
;             if (s == l) v += dsk * __builtin_amdgcn_rcpf(sDt[l * 8 + hh]);
;             sM[lp * 136 + s] = f2bf(v);
.LBB0_1686:
	s_or_b64 exec, exec, s[74:75]
	v_cvt_pk_bf16_f32 v19, v19, s0
	v_readlane_b32 s52, v255, 45
	ds_write_b16 v219, v19 offset:25600
	v_mov_b32_e32 v19, 0
	v_readlane_b32 s53, v255, 46
	s_and_saveexec_b64 s[74:75], s[52:53]
	s_cbranch_execz .LBB0_1688
	v_sub_f32_e32 v18, v36, v18
	v_mul_f32_e32 v18, 0x3fb8aa3b, v18
	v_exp_f32_e32 v18, v18
	s_nop 0
	v_mul_f32_e32 v19, v15, v18

; __device__ __forceinline__ bf f2bf(float f) { return (bf)(pk2(f, 0.f) & 0xFFFFu); }
; __device__ __forceinline__ void ssd_pass2(const Params& p, int layer, int task, char* sm) {
;     ...
;       for (int j = 0; j < 2; j++) {
;         const int s = 64 * wc + 32 * j + r32;
;         if (s < nS) {
;           const float as = sAcs[s * 8 + hh];
; #pragma unroll
;           for (int r = 0; r < 16; r++) {
;             const int lp = 32 * wr + 8 * (r >> 2) + 4 * h5 + (r & 3); const int l = 64 * lh + lp;
;             float v = 0.f;
;             if (s <= l) v = cb[j][r] * __expf(sAcs[l * 8 + hh] - as);
;             if (s == l) v += dsk * __builtin_amdgcn_rcpf(sDt[l * 8 + hh]);
;             sM[lp * 136 + s] = f2bf(v);
.LBB0_1691:
	s_or_b64 exec, exec, vcc
	s_and_saveexec_b64 vcc, s[22:23]
	s_cbranch_execz .LBB0_1757
	v_lshl_add_u32 v17, s78, 2, v245
	ds_read_b32 v17, v17
	v_readlane_b32 s52, v255, 49
	s_waitcnt lgkmcnt(0)
	v_mov_b32_e32 v18, 0
	v_lshl_add_u32 v19, s78, 2, v229
	v_readlane_b32 s53, v255, 50
	s_and_saveexec_b64 s[74:75], s[52:53]
	s_cbranch_execz .LBB0_1694
	v_sub_f32_e32 v18, v21, v17
	v_mul_f32_e32 v18, 0x3fb8aa3b, v18
	v_exp_f32_e32 v18, v18
	s_nop 0
	v_mul_f32_e32 v18, v186, v18

; __device__ __forceinline__ bf f2bf(float f) { return (bf)(pk2(f, 0.f) & 0xFFFFu); }
; __device__ __forceinline__ void ssd_pass2(const Params& p, int layer, int task, char* sm) {
;     ...
;           for (int r = 0; r < 16; r++) {
;             const int lp = 32 * wr + 8 * (r >> 2) + 4 * h5 + (r & 3); const int l = 64 * lh + lp;
;             float v = 0.f;
;             if (s <= l) v = cb[j][r] * __expf(sAcs[l * 8 + hh] - as);
;             if (s == l) v += dsk * __builtin_amdgcn_rcpf(sDt[l * 8 + hh]);
;             sM[lp * 136 + s] = f2bf(v);
.LBB0_1696:
	s_or_b64 exec, exec, s[74:75]
	v_cvt_pk_bf16_f32 v18, v18, s0
	v_readlane_b32 s52, v255, 53
	ds_write_b16 v190, v18 offset:25664
	v_mov_b32_e32 v18, 0
	v_lshl_add_u32 v19, s78, 2, v230
	v_readlane_b32 s53, v255, 54
	s_and_saveexec_b64 s[74:75], s[52:53]
	s_cbranch_execz .LBB0_1698
	v_sub_f32_e32 v18, v22, v17
	v_mul_f32_e32 v18, 0x3fb8aa3b, v18
	v_exp_f32_e32 v18, v18
	s_nop 0
	v_mul_f32_e32 v18, v185, v18

; __device__ __forceinline__ bf f2bf(float f) { return (bf)(pk2(f, 0.f) & 0xFFFFu); }
; __device__ __forceinline__ void ssd_pass2(const Params& p, int layer, int task, char* sm) {
;     ...
;           for (int r = 0; r < 16; r++) {
;             const int lp = 32 * wr + 8 * (r >> 2) + 4 * h5 + (r & 3); const int l = 64 * lh + lp;
;             float v = 0.f;
;             if (s <= l) v = cb[j][r] * __expf(sAcs[l * 8 + hh] - as);
;             if (s == l) v += dsk * __builtin_amdgcn_rcpf(sDt[l * 8 + hh]);
;             sM[lp * 136 + s] = f2bf(v);
.LBB0_1700:
	s_or_b64 exec, exec, s[74:75]
	v_cvt_pk_bf16_f32 v18, v18, s0
	v_readlane_b32 s52, v255, 57
	ds_write_b16 v191, v18 offset:25664
	v_mov_b32_e32 v18, 0
	v_lshl_add_u32 v19, s78, 2, v231
	v_readlane_b32 s53, v255, 58
	s_and_saveexec_b64 s[74:75], s[52:53]
	s_cbranch_execz .LBB0_1702
	v_sub_f32_e32 v18, v23, v17
	v_mul_f32_e32 v18, 0x3fb8aa3b, v18
	v_exp_f32_e32 v18, v18
	s_nop 0
	v_mul_f32_e32 v18, v184, v18

; __device__ __forceinline__ bf f2bf(float f) { return (bf)(pk2(f, 0.f) & 0xFFFFu); }
; __device__ __forceinline__ void ssd_pass2(const Params& p, int layer, int task, char* sm) {
;     ...
;           for (int r = 0; r < 16; r++) {
;             const int lp = 32 * wr + 8 * (r >> 2) + 4 * h5 + (r & 3); const int l = 64 * lh + lp;
;             float v = 0.f;
;             if (s <= l) v = cb[j][r] * __expf(sAcs[l * 8 + hh] - as);
;             if (s == l) v += dsk * __builtin_amdgcn_rcpf(sDt[l * 8 + hh]);
;             sM[lp * 136 + s] = f2bf(v);
.LBB0_1704:
	s_or_b64 exec, exec, s[74:75]
	v_cvt_pk_bf16_f32 v18, v18, s0
	v_readlane_b32 s52, v255, 61
	ds_write_b16 v192, v18 offset:25664
	v_mov_b32_e32 v18, 0
	v_lshl_add_u32 v19, s78, 2, v232
	v_readlane_b32 s53, v255, 62
	s_and_saveexec_b64 s[74:75], s[52:53]
	s_cbranch_execz .LBB0_1706
	v_sub_f32_e32 v18, v24, v17
	v_mul_f32_e32 v18, 0x3fb8aa3b, v18
	v_exp_f32_e32 v18, v18
	s_nop 0
	v_mul_f32_e32 v18, v183, v18

; __device__ __forceinline__ bf f2bf(float f) { return (bf)(pk2(f, 0.f) & 0xFFFFu); }
; __device__ __forceinline__ void ssd_pass2(const Params& p, int layer, int task, char* sm) {
;     ...
;           for (int r = 0; r < 16; r++) {
;             const int lp = 32 * wr + 8 * (r >> 2) + 4 * h5 + (r & 3); const int l = 64 * lh + lp;
;             float v = 0.f;
;             if (s <= l) v = cb[j][r] * __expf(sAcs[l * 8 + hh] - as);
;             if (s == l) v += dsk * __builtin_amdgcn_rcpf(sDt[l * 8 + hh]);
;             sM[lp * 136 + s] = f2bf(v);
.LBB0_1708:
	s_or_b64 exec, exec, s[74:75]
	v_cvt_pk_bf16_f32 v18, v18, s0
	ds_write_b16 v193, v18 offset:25664
	v_mov_b32_e32 v18, 0
	v_lshl_add_u32 v19, s78, 2, v233
	s_and_saveexec_b64 s[74:75], s[88:89]
	s_cbranch_execz .LBB0_1710
	v_sub_f32_e32 v18, v25, v17
	v_mul_f32_e32 v18, 0x3fb8aa3b, v18
	v_exp_f32_e32 v18, v18
	s_nop 0
	v_mul_f32_e32 v18, v182, v18

; __device__ __forceinline__ bf f2bf(float f) { return (bf)(pk2(f, 0.f) & 0xFFFFu); }
; __device__ __forceinline__ void ssd_pass2(const Params& p, int layer, int task, char* sm) {
;     ...
;           for (int r = 0; r < 16; r++) {
;             const int lp = 32 * wr + 8 * (r >> 2) + 4 * h5 + (r & 3); const int l = 64 * lh + lp;
;             float v = 0.f;
;             if (s <= l) v = cb[j][r] * __expf(sAcs[l * 8 + hh] - as);
;             if (s == l) v += dsk * __builtin_amdgcn_rcpf(sDt[l * 8 + hh]);
;             sM[lp * 136 + s] = f2bf(v);
.LBB0_1712:
	s_or_b64 exec, exec, s[74:75]
	v_cvt_pk_bf16_f32 v18, v18, s0
	ds_write_b16 v194, v18 offset:25664
	v_mov_b32_e32 v18, 0
	v_lshl_add_u32 v19, s78, 2, v234
	s_and_saveexec_b64 s[74:75], s[92:93]
	s_cbranch_execz .LBB0_1714
	v_sub_f32_e32 v18, v26, v17
	v_mul_f32_e32 v18, 0x3fb8aa3b, v18
	v_exp_f32_e32 v18, v18
	s_nop 0
	v_mul_f32_e32 v18, v181, v18

; __device__ __forceinline__ bf f2bf(float f) { return (bf)(pk2(f, 0.f) & 0xFFFFu); }
; __device__ __forceinline__ void ssd_pass2(const Params& p, int layer, int task, char* sm) {
;     ...
;           for (int r = 0; r < 16; r++) {
;             const int lp = 32 * wr + 8 * (r >> 2) + 4 * h5 + (r & 3); const int l = 64 * lh + lp;
;             float v = 0.f;
;             if (s <= l) v = cb[j][r] * __expf(sAcs[l * 8 + hh] - as);
;             if (s == l) v += dsk * __builtin_amdgcn_rcpf(sDt[l * 8 + hh]);
;             sM[lp * 136 + s] = f2bf(v);
.LBB0_1716:
	s_or_b64 exec, exec, s[74:75]
	v_cvt_pk_bf16_f32 v18, v18, s0
	ds_write_b16 v195, v18 offset:25664
	v_mov_b32_e32 v18, 0
	v_lshl_add_u32 v19, s78, 2, v235
	s_and_saveexec_b64 s[74:75], s[96:97]
	s_cbranch_execz .LBB0_1718
	v_sub_f32_e32 v18, v27, v17
	v_mul_f32_e32 v18, 0x3fb8aa3b, v18
	v_exp_f32_e32 v18, v18
	s_nop 0
	v_mul_f32_e32 v18, v180, v18

; __device__ __forceinline__ bf f2bf(float f) { return (bf)(pk2(f, 0.f) & 0xFFFFu); }
; __device__ __forceinline__ void ssd_pass2(const Params& p, int layer, int task, char* sm) {
;     ...
;           for (int r = 0; r < 16; r++) {
;             const int lp = 32 * wr + 8 * (r >> 2) + 4 * h5 + (r & 3); const int l = 64 * lh + lp;
;             float v = 0.f;
;             if (s <= l) v = cb[j][r] * __expf(sAcs[l * 8 + hh] - as);
;             if (s == l) v += dsk * __builtin_amdgcn_rcpf(sDt[l * 8 + hh]);
;             sM[lp * 136 + s] = f2bf(v);
.LBB0_1720:
	s_or_b64 exec, exec, s[74:75]
	v_cvt_pk_bf16_f32 v18, v18, s0
	ds_write_b16 v196, v18 offset:25664
	v_mov_b32_e32 v18, 0
	v_lshl_add_u32 v19, s78, 2, v236
	s_and_saveexec_b64 s[74:75], s[10:11]
	s_cbranch_execz .LBB0_1722
	v_sub_f32_e32 v18, v28, v17
	v_mul_f32_e32 v18, 0x3fb8aa3b, v18
	v_exp_f32_e32 v18, v18
	s_nop 0
	v_mul_f32_e32 v18, v179, v18

; __device__ __forceinline__ bf f2bf(float f) { return (bf)(pk2(f, 0.f) & 0xFFFFu); }
; __device__ __forceinline__ void ssd_pass2(const Params& p, int layer, int task, char* sm) {
;     ...
;           for (int r = 0; r < 16; r++) {
;             const int lp = 32 * wr + 8 * (r >> 2) + 4 * h5 + (r & 3); const int l = 64 * lh + lp;
;             float v = 0.f;
;             if (s <= l) v = cb[j][r] * __expf(sAcs[l * 8 + hh] - as);
;             if (s == l) v += dsk * __builtin_amdgcn_rcpf(sDt[l * 8 + hh]);
;             sM[lp * 136 + s] = f2bf(v);
.LBB0_1724:
	s_or_b64 exec, exec, s[74:75]
	v_cvt_pk_bf16_f32 v18, v18, s0
	ds_write_b16 v197, v18 offset:25664
	v_mov_b32_e32 v18, 0
	v_lshl_add_u32 v19, s78, 2, v237
	s_and_saveexec_b64 s[74:75], s[14:15]
	s_cbranch_execz .LBB0_1726
	v_sub_f32_e32 v18, v29, v17
	v_mul_f32_e32 v18, 0x3fb8aa3b, v18
	v_exp_f32_e32 v18, v18
	s_nop 0
	v_mul_f32_e32 v18, v178, v18

; __device__ __forceinline__ bf f2bf(float f) { return (bf)(pk2(f, 0.f) & 0xFFFFu); }
; __device__ __forceinline__ void ssd_pass2(const Params& p, int layer, int task, char* sm) {
;     ...
;           for (int r = 0; r < 16; r++) {
;             const int lp = 32 * wr + 8 * (r >> 2) + 4 * h5 + (r & 3); const int l = 64 * lh + lp;
;             float v = 0.f;
;             if (s <= l) v = cb[j][r] * __expf(sAcs[l * 8 + hh] - as);
;             if (s == l) v += dsk * __builtin_amdgcn_rcpf(sDt[l * 8 + hh]);
;             sM[lp * 136 + s] = f2bf(v);
.LBB0_1728:
	s_or_b64 exec, exec, s[74:75]
	v_cvt_pk_bf16_f32 v18, v18, s0
	ds_write_b16 v213, v18 offset:25664
	v_mov_b32_e32 v18, 0
	v_lshl_add_u32 v19, s78, 2, v238
	s_and_saveexec_b64 s[74:75], s[18:19]
	s_cbranch_execz .LBB0_1730
	v_sub_f32_e32 v18, v30, v17
	v_mul_f32_e32 v18, 0x3fb8aa3b, v18
	v_exp_f32_e32 v18, v18
	s_nop 0
	v_mul_f32_e32 v18, v177, v18

; __device__ __forceinline__ bf f2bf(float f) { return (bf)(pk2(f, 0.f) & 0xFFFFu); }
; __device__ __forceinline__ void ssd_pass2(const Params& p, int layer, int task, char* sm) {
;     ...
;           for (int r = 0; r < 16; r++) {
;             const int lp = 32 * wr + 8 * (r >> 2) + 4 * h5 + (r & 3); const int l = 64 * lh + lp;
;             float v = 0.f;
;             if (s <= l) v = cb[j][r] * __expf(sAcs[l * 8 + hh] - as);
;             if (s == l) v += dsk * __builtin_amdgcn_rcpf(sDt[l * 8 + hh]);
;             sM[lp * 136 + s] = f2bf(v);
.LBB0_1732:
	s_or_b64 exec, exec, s[74:75]
	v_cvt_pk_bf16_f32 v18, v18, s0
	ds_write_b16 v214, v18 offset:25664
	v_mov_b32_e32 v18, 0
	v_lshl_add_u32 v19, s78, 2, v239
	s_and_saveexec_b64 s[74:75], s[24:25]
	s_cbranch_execz .LBB0_1734
	v_sub_f32_e32 v18, v31, v17
	v_mul_f32_e32 v18, 0x3fb8aa3b, v18
	v_exp_f32_e32 v18, v18
	s_nop 0
	v_mul_f32_e32 v18, v176, v18

; __device__ __forceinline__ bf f2bf(float f) { return (bf)(pk2(f, 0.f) & 0xFFFFu); }
; __device__ __forceinline__ void ssd_pass2(const Params& p, int layer, int task, char* sm) {
;     ...
;           for (int r = 0; r < 16; r++) {
;             const int lp = 32 * wr + 8 * (r >> 2) + 4 * h5 + (r & 3); const int l = 64 * lh + lp;
;             float v = 0.f;
;             if (s <= l) v = cb[j][r] * __expf(sAcs[l * 8 + hh] - as);
;             if (s == l) v += dsk * __builtin_amdgcn_rcpf(sDt[l * 8 + hh]);
;             sM[lp * 136 + s] = f2bf(v);
.LBB0_1736:
	s_or_b64 exec, exec, s[74:75]
	v_cvt_pk_bf16_f32 v18, v18, s0
	ds_write_b16 v215, v18 offset:25664
	v_mov_b32_e32 v18, 0
	v_lshl_add_u32 v19, s78, 2, v240
	s_and_saveexec_b64 s[74:75], s[28:29]
	s_cbranch_execz .LBB0_1738
	v_sub_f32_e32 v18, v32, v17
	v_mul_f32_e32 v18, 0x3fb8aa3b, v18
	v_exp_f32_e32 v18, v18
	s_nop 0
	v_mul_f32_e32 v18, v175, v18

; __device__ __forceinline__ bf f2bf(float f) { return (bf)(pk2(f, 0.f) & 0xFFFFu); }
; __device__ __forceinline__ void ssd_pass2(const Params& p, int layer, int task, char* sm) {
;     ...
;           for (int r = 0; r < 16; r++) {
;             const int lp = 32 * wr + 8 * (r >> 2) + 4 * h5 + (r & 3); const int l = 64 * lh + lp;
;             float v = 0.f;
;             if (s <= l) v = cb[j][r] * __expf(sAcs[l * 8 + hh] - as);
;             if (s == l) v += dsk * __builtin_amdgcn_rcpf(sDt[l * 8 + hh]);
;             sM[lp * 136 + s] = f2bf(v);
.LBB0_1740:
	s_or_b64 exec, exec, s[74:75]
	v_cvt_pk_bf16_f32 v18, v18, s0
	ds_write_b16 v216, v18 offset:25664
	v_mov_b32_e32 v18, 0
	v_lshl_add_u32 v19, s78, 2, v241
	s_and_saveexec_b64 s[74:75], s[34:35]
	s_cbranch_execz .LBB0_1742
	v_sub_f32_e32 v18, v33, v17
	v_mul_f32_e32 v18, 0x3fb8aa3b, v18
	v_exp_f32_e32 v18, v18
	s_nop 0
	v_mul_f32_e32 v18, v174, v18

; __device__ __forceinline__ bf f2bf(float f) { return (bf)(pk2(f, 0.f) & 0xFFFFu); }
; __device__ __forceinline__ void ssd_pass2(const Params& p, int layer, int task, char* sm) {
;     ...
;           for (int r = 0; r < 16; r++) {
;             const int lp = 32 * wr + 8 * (r >> 2) + 4 * h5 + (r & 3); const int l = 64 * lh + lp;
;             float v = 0.f;
;             if (s <= l) v = cb[j][r] * __expf(sAcs[l * 8 + hh] - as);
;             if (s == l) v += dsk * __builtin_amdgcn_rcpf(sDt[l * 8 + hh]);
;             sM[lp * 136 + s] = f2bf(v);
.LBB0_1744:
	s_or_b64 exec, exec, s[74:75]
	v_cvt_pk_bf16_f32 v18, v18, s0
	ds_write_b16 v217, v18 offset:25664
	v_mov_b32_e32 v18, 0
	v_lshl_add_u32 v19, s78, 2, v242
	s_and_saveexec_b64 s[74:75], s[38:39]
	s_cbranch_execz .LBB0_1746
	v_sub_f32_e32 v18, v34, v17
	v_mul_f32_e32 v18, 0x3fb8aa3b, v18
	v_exp_f32_e32 v18, v18
	s_nop 0
	v_mul_f32_e32 v18, v173, v18

; __device__ __forceinline__ bf f2bf(float f) { return (bf)(pk2(f, 0.f) & 0xFFFFu); }
; __device__ __forceinline__ void ssd_pass2(const Params& p, int layer, int task, char* sm) {
;     ...
;           for (int r = 0; r < 16; r++) {
;             const int lp = 32 * wr + 8 * (r >> 2) + 4 * h5 + (r & 3); const int l = 64 * lh + lp;
;             float v = 0.f;
;             if (s <= l) v = cb[j][r] * __expf(sAcs[l * 8 + hh] - as);
;             if (s == l) v += dsk * __builtin_amdgcn_rcpf(sDt[l * 8 + hh]);
;             sM[lp * 136 + s] = f2bf(v);
.LBB0_1748:
	s_or_b64 exec, exec, s[74:75]
	v_cvt_pk_bf16_f32 v18, v18, s0
	ds_write_b16 v218, v18 offset:25664
	v_mov_b32_e32 v18, 0
	v_lshl_add_u32 v19, s78, 2, v243
	s_and_saveexec_b64 s[74:75], s[42:43]
	s_cbranch_execz .LBB0_1750
	v_sub_f32_e32 v18, v35, v17
	v_mul_f32_e32 v18, 0x3fb8aa3b, v18
	v_exp_f32_e32 v18, v18
	s_nop 0
	v_mul_f32_e32 v18, v172, v18

; __device__ __forceinline__ bf f2bf(float f) { return (bf)(pk2(f, 0.f) & 0xFFFFu); }
; __device__ __forceinline__ void ssd_pass2(const Params& p, int layer, int task, char* sm) {
;     ...
;           for (int r = 0; r < 16; r++) {
;             const int lp = 32 * wr + 8 * (r >> 2) + 4 * h5 + (r & 3); const int l = 64 * lh + lp;
;             float v = 0.f;
;             if (s <= l) v = cb[j][r] * __expf(sAcs[l * 8 + hh] - as);
;             if (s == l) v += dsk * __builtin_amdgcn_rcpf(sDt[l * 8 + hh]);
;             sM[lp * 136 + s] = f2bf(v);
.LBB0_1752:
	s_or_b64 exec, exec, s[74:75]
	v_cvt_pk_bf16_f32 v18, v18, s0
	ds_write_b16 v219, v18 offset:25664
	v_mov_b32_e32 v18, 0
	v_lshl_add_u32 v19, s78, 2, v244
	s_and_saveexec_b64 s[74:75], s[46:47]
	s_cbranch_execz .LBB0_1754
	v_sub_f32_e32 v17, v36, v17
	v_mul_f32_e32 v17, 0x3fb8aa3b, v17
	v_exp_f32_e32 v17, v17
	s_nop 0
	v_mul_f32_e32 v18, v171, v17

; __device__ __forceinline__ bf f2bf(float f) { return (bf)(pk2(f, 0.f) & 0xFFFFu); }
; __device__ __forceinline__ void ssd_pass2(const Params& p, int layer, int task, char* sm) {
;     ...
;     {
;       const float* pv = p.ST + (((size_t)(b * 128 + c) * 16 + hd) * 64 + 32 * wc2 + r32) * 128 + 8 * h5;
; #pragma unroll
;       for (int ks = 0; ks < 8; ks++) {
;         float4 u0 = *(const float4*)(pv + ks * 16), u1 = *(const float4*)(pv + ks * 16 + 4);
;         unsigned q0 = pk2(u0.x, u0.y), q1 = pk2(u0.z, u0.w), q2 = pk2(u1.x, u1.y), q3 = pk2(u1.z, u1.w);
;         pfr[ks][0] = (short)(q0 & 0xFFFF); pfr[ks][1] = (short)(q0 >> 16); pfr[ks][2] = (short)(q1 & 0xFFFF); pfr[ks][3] = (short)(q1 >> 16);
;         pfr[ks][4] = (short)(q2 & 0xFFFF); pfr[ks][5] = (short)(q2 >> 16); pfr[ks][6] = (short)(q3 & 0xFFFF); pfr[ks][7] = (short)(q3 >> 16);
;       }
;     }
;     {
;       const float dsk = p.ssd_d[layer * 16 + hd];
; #pragma unroll
;       for (int j = 0; j < 2; j++) {
;         const int s = 64 * wc + 32 * j + r32;
;         if (s < nS) {
;           const float as = sAcs[s * 8 + hh];
; #pragma unroll
;           for (int r = 0; r < 16; r++) {
;             const int lp = 32 * wr + 8 * (r >> 2) + 4 * h5 + (r & 3); const int l = 64 * lh + lp;
;             float v = 0.f;
;             if (s <= l) v = cb[j][r] * __expf(sAcs[l * 8 + hh] - as);
;             if (s == l) v += dsk * __builtin_amdgcn_rcpf(sDt[l * 8 + hh]);
;             sM[lp * 136 + s] = f2bf(v);
.LBB0_1874:
	s_or_b32 s78, s86, s87
	s_lshl_b32 s68, s78, 6
	v_lshl_add_u64 v[16:17], v[112:113], 0, s[68:69]
	v_lshlrev_b64 v[16:17], 9, v[16:17]
	v_lshl_add_u64 v[16:17], v[114:115], 0, v[16:17]
	global_load_dwordx4 v[100:103], v[16:17], off offset:16
	global_load_dwordx4 v[108:111], v[16:17], off
	global_load_dwordx4 v[92:95], v[16:17], off offset:80
	global_load_dwordx4 v[104:107], v[16:17], off offset:64
	global_load_dwordx4 v[84:87], v[16:17], off offset:144
	global_load_dwordx4 v[96:99], v[16:17], off offset:128
	global_load_dwordx4 v[76:79], v[16:17], off offset:208
	global_load_dwordx4 v[88:91], v[16:17], off offset:192
	global_load_dwordx4 v[68:71], v[16:17], off offset:272
	global_load_dwordx4 v[80:83], v[16:17], off offset:256
	global_load_dwordx4 v[60:63], v[16:17], off offset:336
	global_load_dwordx4 v[72:75], v[16:17], off offset:320
	global_load_dwordx4 v[52:55], v[16:17], off offset:400
	global_load_dwordx4 v[64:67], v[16:17], off offset:384
	global_load_dwordx4 v[48:51], v[16:17], off offset:464
	global_load_dwordx4 v[56:59], v[16:17], off offset:448
	v_readlane_b32 s52, v254, 26
	s_or_b32 s78, s78, s52
	s_mov_b32 s79, s69
	v_readlane_b32 s52, v252, 32
	s_lshl_b64 s[78:79], s[78:79], 2
	v_readlane_b32 s58, v252, 38
	v_readlane_b32 s59, v252, 39
	s_add_u32 s78, s58, s78
	s_addc_u32 s79, s59, s79
	global_load_dword v16, v145, s[78:79]
	v_readlane_b32 s53, v252, 33
	v_readlane_b32 s54, v252, 34
	v_readlane_b32 s55, v252, 35
	v_readlane_b32 s56, v252, 36
	v_readlane_b32 s57, v252, 37
	v_readlane_b32 s60, v252, 40
	v_readlane_b32 s61, v252, 41
	v_readlane_b32 s62, v252, 42
	v_readlane_b32 s63, v252, 43
	v_readlane_b32 s64, v252, 44
	v_readlane_b32 s65, v252, 45
	v_readlane_b32 s66, v252, 46
	v_readlane_b32 s67, v252, 47
	v_lshl_add_u32 v21, s86, 2, v229
	v_lshl_add_u32 v22, s86, 2, v230
	v_lshl_add_u32 v23, s86, 2, v231
	v_lshl_add_u32 v24, s86, 2, v232
	v_lshl_add_u32 v25, s86, 2, v233
	v_lshl_add_u32 v26, s86, 2, v234
	v_lshl_add_u32 v27, s86, 2, v235
	v_lshl_add_u32 v28, s86, 2, v236
	v_lshl_add_u32 v29, s86, 2, v237
	v_lshl_add_u32 v30, s86, 2, v238
	v_lshl_add_u32 v31, s86, 2, v239
	v_lshl_add_u32 v32, s86, 2, v240
	v_lshl_add_u32 v33, s86, 2, v241
	v_lshl_add_u32 v34, s86, 2, v242
	v_lshl_add_u32 v35, s86, 2, v243
	v_lshl_add_u32 v36, s86, 2, v244
	ds_read_b32 v21, v21
	ds_read_b32 v22, v22
	ds_read_b32 v23, v23
	ds_read_b32 v24, v24
	ds_read_b32 v25, v25
	ds_read_b32 v26, v26
	ds_read_b32 v27, v27
	ds_read_b32 v28, v28
	ds_read_b32 v29, v29
	ds_read_b32 v30, v30
	ds_read_b32 v31, v31
	ds_read_b32 v32, v32
	ds_read_b32 v33, v33
	ds_read_b32 v34, v34
	ds_read_b32 v35, v35
	ds_read_b32 v36, v36
	s_waitcnt lgkmcnt(0)
	s_and_saveexec_b64 vcc, s[6:7]
	s_cbranch_execz .LBB0_1940
	v_add_u32_e32 v17, s86, v189
	v_lshl_add_u32 v17, v17, 2, s84
	ds_read_b32 v18, v17
	s_waitcnt lgkmcnt(0)
	v_readlane_b32 s52, v254, 48
	v_mov_b32_e32 v19, 0
	v_readlane_b32 s53, v254, 49
	s_and_saveexec_b64 s[78:79], s[52:53]
	s_cbranch_execz .LBB0_1877
	v_sub_f32_e32 v19, v21, v18
	v_mul_f32_e32 v19, 0x3fb8aa3b, v19
	v_exp_f32_e32 v19, v19
	s_nop 0
	v_mul_f32_e32 v19, v0, v19

; __device__ __forceinline__ bf f2bf(float f) { return (bf)(pk2(f, 0.f) & 0xFFFFu); }
; __device__ __forceinline__ void ssd_pass2(const Params& p, int layer, int task, char* sm) {
;     ...
;           for (int r = 0; r < 16; r++) {
;             const int lp = 32 * wr + 8 * (r >> 2) + 4 * h5 + (r & 3); const int l = 64 * lh + lp;
;             float v = 0.f;
;             if (s <= l) v = cb[j][r] * __expf(sAcs[l * 8 + hh] - as);
;             if (s == l) v += dsk * __builtin_amdgcn_rcpf(sDt[l * 8 + hh]);
;             sM[lp * 136 + s] = f2bf(v);
.LBB0_1879:
	s_or_b64 exec, exec, s[78:79]
	v_cvt_pk_bf16_f32 v19, v19, s0
	v_readlane_b32 s52, v254, 52
	ds_write_b16 v190, v19 offset:25600
	v_mov_b32_e32 v19, 0
	v_readlane_b32 s53, v254, 53
	s_and_saveexec_b64 s[78:79], s[52:53]
	s_cbranch_execz .LBB0_1881
	v_sub_f32_e32 v19, v22, v18
	v_mul_f32_e32 v19, 0x3fb8aa3b, v19
	v_exp_f32_e32 v19, v19
	s_nop 0
	v_mul_f32_e32 v19, v1, v19

; __device__ __forceinline__ bf f2bf(float f) { return (bf)(pk2(f, 0.f) & 0xFFFFu); }
; __device__ __forceinline__ void ssd_pass2(const Params& p, int layer, int task, char* sm) {
;     ...
;           for (int r = 0; r < 16; r++) {
;             const int lp = 32 * wr + 8 * (r >> 2) + 4 * h5 + (r & 3); const int l = 64 * lh + lp;
;             float v = 0.f;
;             if (s <= l) v = cb[j][r] * __expf(sAcs[l * 8 + hh] - as);
;             if (s == l) v += dsk * __builtin_amdgcn_rcpf(sDt[l * 8 + hh]);
;             sM[lp * 136 + s] = f2bf(v);
.LBB0_1883:
	s_or_b64 exec, exec, s[78:79]
	v_cvt_pk_bf16_f32 v19, v19, s0
	v_readlane_b32 s52, v254, 56
	ds_write_b16 v191, v19 offset:25600
	v_mov_b32_e32 v19, 0
	v_readlane_b32 s53, v254, 57
	s_and_saveexec_b64 s[78:79], s[52:53]
	s_cbranch_execz .LBB0_1885
	v_sub_f32_e32 v19, v23, v18
	v_mul_f32_e32 v19, 0x3fb8aa3b, v19
	v_exp_f32_e32 v19, v19
	s_nop 0
	v_mul_f32_e32 v19, v2, v19

; __device__ __forceinline__ bf f2bf(float f) { return (bf)(pk2(f, 0.f) & 0xFFFFu); }
; __device__ __forceinline__ void ssd_pass2(const Params& p, int layer, int task, char* sm) {
;     ...
;           for (int r = 0; r < 16; r++) {
;             const int lp = 32 * wr + 8 * (r >> 2) + 4 * h5 + (r & 3); const int l = 64 * lh + lp;
;             float v = 0.f;
;             if (s <= l) v = cb[j][r] * __expf(sAcs[l * 8 + hh] - as);
;             if (s == l) v += dsk * __builtin_amdgcn_rcpf(sDt[l * 8 + hh]);
;             sM[lp * 136 + s] = f2bf(v);
.LBB0_1887:
	s_or_b64 exec, exec, s[78:79]
	v_cvt_pk_bf16_f32 v19, v19, s0
	v_readlane_b32 s52, v254, 60
	ds_write_b16 v192, v19 offset:25600
	v_mov_b32_e32 v19, 0
	v_readlane_b32 s53, v254, 61
	s_and_saveexec_b64 s[78:79], s[52:53]
	s_cbranch_execz .LBB0_1889
	v_sub_f32_e32 v19, v24, v18
	v_mul_f32_e32 v19, 0x3fb8aa3b, v19
	v_exp_f32_e32 v19, v19
	s_nop 0
	v_mul_f32_e32 v19, v3, v19

; __device__ __forceinline__ bf f2bf(float f) { return (bf)(pk2(f, 0.f) & 0xFFFFu); }
; __device__ __forceinline__ void ssd_pass2(const Params& p, int layer, int task, char* sm) {
;     ...
;           for (int r = 0; r < 16; r++) {
;             const int lp = 32 * wr + 8 * (r >> 2) + 4 * h5 + (r & 3); const int l = 64 * lh + lp;
;             float v = 0.f;
;             if (s <= l) v = cb[j][r] * __expf(sAcs[l * 8 + hh] - as);
;             if (s == l) v += dsk * __builtin_amdgcn_rcpf(sDt[l * 8 + hh]);
;             sM[lp * 136 + s] = f2bf(v);
.LBB0_1891:
	s_or_b64 exec, exec, s[78:79]
	v_cvt_pk_bf16_f32 v19, v19, s0
	v_readlane_b32 s52, v255, 1
	ds_write_b16 v193, v19 offset:25600
	v_mov_b32_e32 v19, 0
	v_readlane_b32 s53, v255, 2
	s_and_saveexec_b64 s[78:79], s[52:53]
	s_cbranch_execz .LBB0_1893
	v_sub_f32_e32 v19, v25, v18
	v_mul_f32_e32 v19, 0x3fb8aa3b, v19
	v_exp_f32_e32 v19, v19
	s_nop 0
	v_mul_f32_e32 v19, v4, v19

; __device__ __forceinline__ bf f2bf(float f) { return (bf)(pk2(f, 0.f) & 0xFFFFu); }
; __device__ __forceinline__ void ssd_pass2(const Params& p, int layer, int task, char* sm) {
;     ...
;           for (int r = 0; r < 16; r++) {
;             const int lp = 32 * wr + 8 * (r >> 2) + 4 * h5 + (r & 3); const int l = 64 * lh + lp;
;             float v = 0.f;
;             if (s <= l) v = cb[j][r] * __expf(sAcs[l * 8 + hh] - as);
;             if (s == l) v += dsk * __builtin_amdgcn_rcpf(sDt[l * 8 + hh]);
;             sM[lp * 136 + s] = f2bf(v);
.LBB0_1895:
	s_or_b64 exec, exec, s[78:79]
	v_cvt_pk_bf16_f32 v19, v19, s0
	v_readlane_b32 s52, v255, 5
	ds_write_b16 v194, v19 offset:25600
	v_mov_b32_e32 v19, 0
	v_readlane_b32 s53, v255, 6
	s_and_saveexec_b64 s[78:79], s[52:53]
	s_cbranch_execz .LBB0_1897
	v_sub_f32_e32 v19, v26, v18
	v_mul_f32_e32 v19, 0x3fb8aa3b, v19
	v_exp_f32_e32 v19, v19
	s_nop 0
	v_mul_f32_e32 v19, v5, v19

; __device__ __forceinline__ bf f2bf(float f) { return (bf)(pk2(f, 0.f) & 0xFFFFu); }
; __device__ __forceinline__ void ssd_pass2(const Params& p, int layer, int task, char* sm) {
;     ...
;           for (int r = 0; r < 16; r++) {
;             const int lp = 32 * wr + 8 * (r >> 2) + 4 * h5 + (r & 3); const int l = 64 * lh + lp;
;             float v = 0.f;
;             if (s <= l) v = cb[j][r] * __expf(sAcs[l * 8 + hh] - as);
;             if (s == l) v += dsk * __builtin_amdgcn_rcpf(sDt[l * 8 + hh]);
;             sM[lp * 136 + s] = f2bf(v);
.LBB0_1899:
	s_or_b64 exec, exec, s[78:79]
	v_cvt_pk_bf16_f32 v19, v19, s0
	v_readlane_b32 s52, v255, 9
	ds_write_b16 v195, v19 offset:25600
	v_mov_b32_e32 v19, 0
	v_readlane_b32 s53, v255, 10
	s_and_saveexec_b64 s[78:79], s[52:53]
	s_cbranch_execz .LBB0_1901
	v_sub_f32_e32 v19, v27, v18
	v_mul_f32_e32 v19, 0x3fb8aa3b, v19
	v_exp_f32_e32 v19, v19
	s_nop 0
	v_mul_f32_e32 v19, v6, v19

; __device__ __forceinline__ bf f2bf(float f) { return (bf)(pk2(f, 0.f) & 0xFFFFu); }
; __device__ __forceinline__ void ssd_pass2(const Params& p, int layer, int task, char* sm) {
;     ...
;           for (int r = 0; r < 16; r++) {
;             const int lp = 32 * wr + 8 * (r >> 2) + 4 * h5 + (r & 3); const int l = 64 * lh + lp;
;             float v = 0.f;
;             if (s <= l) v = cb[j][r] * __expf(sAcs[l * 8 + hh] - as);
;             if (s == l) v += dsk * __builtin_amdgcn_rcpf(sDt[l * 8 + hh]);
;             sM[lp * 136 + s] = f2bf(v);
.LBB0_1903:
	s_or_b64 exec, exec, s[78:79]
	v_cvt_pk_bf16_f32 v19, v19, s0
	v_readlane_b32 s52, v255, 13
	ds_write_b16 v196, v19 offset:25600
	v_mov_b32_e32 v19, 0
	v_readlane_b32 s53, v255, 14
	s_and_saveexec_b64 s[78:79], s[52:53]
	s_cbranch_execz .LBB0_1905
	v_sub_f32_e32 v19, v28, v18
	v_mul_f32_e32 v19, 0x3fb8aa3b, v19
	v_exp_f32_e32 v19, v19
	s_nop 0
	v_mul_f32_e32 v19, v7, v19

; __device__ __forceinline__ bf f2bf(float f) { return (bf)(pk2(f, 0.f) & 0xFFFFu); }
; __device__ __forceinline__ void ssd_pass2(const Params& p, int layer, int task, char* sm) {
;     ...
;           for (int r = 0; r < 16; r++) {
;             const int lp = 32 * wr + 8 * (r >> 2) + 4 * h5 + (r & 3); const int l = 64 * lh + lp;
;             float v = 0.f;
;             if (s <= l) v = cb[j][r] * __expf(sAcs[l * 8 + hh] - as);
;             if (s == l) v += dsk * __builtin_amdgcn_rcpf(sDt[l * 8 + hh]);
;             sM[lp * 136 + s] = f2bf(v);
.LBB0_1907:
	s_or_b64 exec, exec, s[78:79]
	v_cvt_pk_bf16_f32 v19, v19, s0
	v_readlane_b32 s52, v255, 17
	ds_write_b16 v197, v19 offset:25600
	v_mov_b32_e32 v19, 0
	v_readlane_b32 s53, v255, 18
	s_and_saveexec_b64 s[78:79], s[52:53]
	s_cbranch_execz .LBB0_1909
	v_sub_f32_e32 v19, v29, v18
	v_mul_f32_e32 v19, 0x3fb8aa3b, v19
	v_exp_f32_e32 v19, v19
	s_nop 0
	v_mul_f32_e32 v19, v8, v19

; __device__ __forceinline__ bf f2bf(float f) { return (bf)(pk2(f, 0.f) & 0xFFFFu); }
; __device__ __forceinline__ void ssd_pass2(const Params& p, int layer, int task, char* sm) {
;     ...
;           for (int r = 0; r < 16; r++) {
;             const int lp = 32 * wr + 8 * (r >> 2) + 4 * h5 + (r & 3); const int l = 64 * lh + lp;
;             float v = 0.f;
;             if (s <= l) v = cb[j][r] * __expf(sAcs[l * 8 + hh] - as);
;             if (s == l) v += dsk * __builtin_amdgcn_rcpf(sDt[l * 8 + hh]);
;             sM[lp * 136 + s] = f2bf(v);
.LBB0_1911:
	s_or_b64 exec, exec, s[78:79]
	v_cvt_pk_bf16_f32 v19, v19, s0
	v_readlane_b32 s52, v255, 21
	ds_write_b16 v213, v19 offset:25600
	v_mov_b32_e32 v19, 0
	v_readlane_b32 s53, v255, 22
	s_and_saveexec_b64 s[78:79], s[52:53]
	s_cbranch_execz .LBB0_1913
	v_sub_f32_e32 v19, v30, v18
	v_mul_f32_e32 v19, 0x3fb8aa3b, v19
	v_exp_f32_e32 v19, v19
	s_nop 0
	v_mul_f32_e32 v19, v9, v19

; __device__ __forceinline__ bf f2bf(float f) { return (bf)(pk2(f, 0.f) & 0xFFFFu); }
; __device__ __forceinline__ void ssd_pass2(const Params& p, int layer, int task, char* sm) {
;     ...
;           for (int r = 0; r < 16; r++) {
;             const int lp = 32 * wr + 8 * (r >> 2) + 4 * h5 + (r & 3); const int l = 64 * lh + lp;
;             float v = 0.f;
;             if (s <= l) v = cb[j][r] * __expf(sAcs[l * 8 + hh] - as);
;             if (s == l) v += dsk * __builtin_amdgcn_rcpf(sDt[l * 8 + hh]);
;             sM[lp * 136 + s] = f2bf(v);
.LBB0_1915:
	s_or_b64 exec, exec, s[78:79]
	v_cvt_pk_bf16_f32 v19, v19, s0
	v_readlane_b32 s52, v255, 25
	ds_write_b16 v214, v19 offset:25600
	v_mov_b32_e32 v19, 0
	v_readlane_b32 s53, v255, 26
	s_and_saveexec_b64 s[78:79], s[52:53]
	s_cbranch_execz .LBB0_1917
	v_sub_f32_e32 v19, v31, v18
	v_mul_f32_e32 v19, 0x3fb8aa3b, v19
	v_exp_f32_e32 v19, v19
	s_nop 0
	v_mul_f32_e32 v19, v10, v19

; __device__ __forceinline__ bf f2bf(float f) { return (bf)(pk2(f, 0.f) & 0xFFFFu); }
; __device__ __forceinline__ void ssd_pass2(const Params& p, int layer, int task, char* sm) {
;     ...
;           for (int r = 0; r < 16; r++) {
;             const int lp = 32 * wr + 8 * (r >> 2) + 4 * h5 + (r & 3); const int l = 64 * lh + lp;
;             float v = 0.f;
;             if (s <= l) v = cb[j][r] * __expf(sAcs[l * 8 + hh] - as);
;             if (s == l) v += dsk * __builtin_amdgcn_rcpf(sDt[l * 8 + hh]);
;             sM[lp * 136 + s] = f2bf(v);
.LBB0_1919:
	s_or_b64 exec, exec, s[78:79]
	v_cvt_pk_bf16_f32 v19, v19, s0
	v_readlane_b32 s52, v255, 29
	ds_write_b16 v215, v19 offset:25600
	v_mov_b32_e32 v19, 0
	v_readlane_b32 s53, v255, 30
	s_and_saveexec_b64 s[78:79], s[52:53]
	s_cbranch_execz .LBB0_1921
	v_sub_f32_e32 v19, v32, v18
	v_mul_f32_e32 v19, 0x3fb8aa3b, v19
	v_exp_f32_e32 v19, v19
	s_nop 0
	v_mul_f32_e32 v19, v11, v19

; __device__ __forceinline__ bf f2bf(float f) { return (bf)(pk2(f, 0.f) & 0xFFFFu); }
; __device__ __forceinline__ void ssd_pass2(const Params& p, int layer, int task, char* sm) {
;     ...
;           for (int r = 0; r < 16; r++) {
;             const int lp = 32 * wr + 8 * (r >> 2) + 4 * h5 + (r & 3); const int l = 64 * lh + lp;
;             float v = 0.f;
;             if (s <= l) v = cb[j][r] * __expf(sAcs[l * 8 + hh] - as);
;             if (s == l) v += dsk * __builtin_amdgcn_rcpf(sDt[l * 8 + hh]);
;             sM[lp * 136 + s] = f2bf(v);
.LBB0_1923:
	s_or_b64 exec, exec, s[78:79]
	v_cvt_pk_bf16_f32 v19, v19, s0
	v_readlane_b32 s52, v255, 33
	ds_write_b16 v216, v19 offset:25600
	v_mov_b32_e32 v19, 0
	v_readlane_b32 s53, v255, 34
	s_and_saveexec_b64 s[78:79], s[52:53]
	s_cbranch_execz .LBB0_1925
	v_sub_f32_e32 v19, v33, v18
	v_mul_f32_e32 v19, 0x3fb8aa3b, v19
	v_exp_f32_e32 v19, v19
	s_nop 0
	v_mul_f32_e32 v19, v12, v19

; __device__ __forceinline__ bf f2bf(float f) { return (bf)(pk2(f, 0.f) & 0xFFFFu); }
; __device__ __forceinline__ void ssd_pass2(const Params& p, int layer, int task, char* sm) {
;     ...
;           for (int r = 0; r < 16; r++) {
;             const int lp = 32 * wr + 8 * (r >> 2) + 4 * h5 + (r & 3); const int l = 64 * lh + lp;
;             float v = 0.f;
;             if (s <= l) v = cb[j][r] * __expf(sAcs[l * 8 + hh] - as);
;             if (s == l) v += dsk * __builtin_amdgcn_rcpf(sDt[l * 8 + hh]);
;             sM[lp * 136 + s] = f2bf(v);
.LBB0_1927:
	s_or_b64 exec, exec, s[78:79]
	v_cvt_pk_bf16_f32 v19, v19, s0
	v_readlane_b32 s52, v255, 37
	ds_write_b16 v217, v19 offset:25600
	v_mov_b32_e32 v19, 0
	v_readlane_b32 s53, v255, 38
	s_and_saveexec_b64 s[78:79], s[52:53]
	s_cbranch_execz .LBB0_1929
	v_sub_f32_e32 v19, v34, v18
	v_mul_f32_e32 v19, 0x3fb8aa3b, v19
	v_exp_f32_e32 v19, v19
	s_nop 0
	v_mul_f32_e32 v19, v13, v19

; __device__ __forceinline__ bf f2bf(float f) { return (bf)(pk2(f, 0.f) & 0xFFFFu); }
; __device__ __forceinline__ void ssd_pass2(const Params& p, int layer, int task, char* sm) {
;     ...
;           for (int r = 0; r < 16; r++) {
;             const int lp = 32 * wr + 8 * (r >> 2) + 4 * h5 + (r & 3); const int l = 64 * lh + lp;
;             float v = 0.f;
;             if (s <= l) v = cb[j][r] * __expf(sAcs[l * 8 + hh] - as);
;             if (s == l) v += dsk * __builtin_amdgcn_rcpf(sDt[l * 8 + hh]);
;             sM[lp * 136 + s] = f2bf(v);
.LBB0_1931:
	s_or_b64 exec, exec, s[78:79]
	v_cvt_pk_bf16_f32 v19, v19, s0
	v_readlane_b32 s52, v255, 41
	ds_write_b16 v218, v19 offset:25600
	v_mov_b32_e32 v19, 0
	v_readlane_b32 s53, v255, 42
	s_and_saveexec_b64 s[78:79], s[52:53]
	s_cbranch_execz .LBB0_1933
	v_sub_f32_e32 v19, v35, v18
	v_mul_f32_e32 v19, 0x3fb8aa3b, v19
	v_exp_f32_e32 v19, v19
	s_nop 0
	v_mul_f32_e32 v19, v14, v19

; __device__ __forceinline__ bf f2bf(float f) { return (bf)(pk2(f, 0.f) & 0xFFFFu); }
; __device__ __forceinline__ void ssd_pass2(const Params& p, int layer, int task, char* sm) {
;     ...
;           for (int r = 0; r < 16; r++) {
;             const int lp = 32 * wr + 8 * (r >> 2) + 4 * h5 + (r & 3); const int l = 64 * lh + lp;
;             float v = 0.f;
;             if (s <= l) v = cb[j][r] * __expf(sAcs[l * 8 + hh] - as);
;             if (s == l) v += dsk * __builtin_amdgcn_rcpf(sDt[l * 8 + hh]);
;             sM[lp * 136 + s] = f2bf(v);
.LBB0_1935:
	s_or_b64 exec, exec, s[78:79]
	v_cvt_pk_bf16_f32 v19, v19, s0
	v_readlane_b32 s52, v255, 45
	ds_write_b16 v219, v19 offset:25600
	v_mov_b32_e32 v19, 0
	v_readlane_b32 s53, v255, 46
	s_and_saveexec_b64 s[78:79], s[52:53]
	s_cbranch_execz .LBB0_1937
	v_sub_f32_e32 v18, v36, v18
	v_mul_f32_e32 v18, 0x3fb8aa3b, v18
	v_exp_f32_e32 v18, v18
	s_nop 0
	v_mul_f32_e32 v19, v15, v18

; __device__ __forceinline__ bf f2bf(float f) { return (bf)(pk2(f, 0.f) & 0xFFFFu); }
; __device__ __forceinline__ void ssd_pass2(const Params& p, int layer, int task, char* sm) {
;     ...
;       for (int j = 0; j < 2; j++) {
;         const int s = 64 * wc + 32 * j + r32;
;         if (s < nS) {
;           const float as = sAcs[s * 8 + hh];
; #pragma unroll
;           for (int r = 0; r < 16; r++) {
;             const int lp = 32 * wr + 8 * (r >> 2) + 4 * h5 + (r & 3); const int l = 64 * lh + lp;
;             float v = 0.f;
;             if (s <= l) v = cb[j][r] * __expf(sAcs[l * 8 + hh] - as);
;             if (s == l) v += dsk * __builtin_amdgcn_rcpf(sDt[l * 8 + hh]);
;             sM[lp * 136 + s] = f2bf(v);
.LBB0_1940:
	s_or_b64 exec, exec, vcc
	s_and_saveexec_b64 vcc, s[22:23]
	s_cbranch_execz .LBB0_2006
	v_lshl_add_u32 v17, s86, 2, v245
	ds_read_b32 v17, v17
	v_readlane_b32 s52, v255, 49
	s_waitcnt lgkmcnt(0)
	v_mov_b32_e32 v18, 0
	v_readlane_b32 s53, v255, 50
	s_and_saveexec_b64 s[78:79], s[52:53]
	s_cbranch_execz .LBB0_1943
	v_sub_f32_e32 v18, v21, v17
	v_mul_f32_e32 v18, 0x3fb8aa3b, v18
	v_exp_f32_e32 v18, v18
	s_nop 0
	v_mul_f32_e32 v18, v186, v18

; __device__ __forceinline__ bf f2bf(float f) { return (bf)(pk2(f, 0.f) & 0xFFFFu); }
; __device__ __forceinline__ void ssd_pass2(const Params& p, int layer, int task, char* sm) {
;     ...
;           for (int r = 0; r < 16; r++) {
;             const int lp = 32 * wr + 8 * (r >> 2) + 4 * h5 + (r & 3); const int l = 64 * lh + lp;
;             float v = 0.f;
;             if (s <= l) v = cb[j][r] * __expf(sAcs[l * 8 + hh] - as);
;             if (s == l) v += dsk * __builtin_amdgcn_rcpf(sDt[l * 8 + hh]);
;             sM[lp * 136 + s] = f2bf(v);
.LBB0_1945:
	s_or_b64 exec, exec, s[78:79]
	v_cvt_pk_bf16_f32 v18, v18, s0
	v_readlane_b32 s52, v255, 53
	ds_write_b16 v190, v18 offset:25664
	v_mov_b32_e32 v18, 0
	v_readlane_b32 s53, v255, 54
	s_and_saveexec_b64 s[78:79], s[52:53]
	s_cbranch_execz .LBB0_1947
	v_sub_f32_e32 v18, v22, v17
	v_mul_f32_e32 v18, 0x3fb8aa3b, v18
	v_exp_f32_e32 v18, v18
	s_nop 0
	v_mul_f32_e32 v18, v185, v18

; __device__ __forceinline__ bf f2bf(float f) { return (bf)(pk2(f, 0.f) & 0xFFFFu); }
; __device__ __forceinline__ void ssd_pass2(const Params& p, int layer, int task, char* sm) {
;     ...
;           for (int r = 0; r < 16; r++) {
;             const int lp = 32 * wr + 8 * (r >> 2) + 4 * h5 + (r & 3); const int l = 64 * lh + lp;
;             float v = 0.f;
;             if (s <= l) v = cb[j][r] * __expf(sAcs[l * 8 + hh] - as);
;             if (s == l) v += dsk * __builtin_amdgcn_rcpf(sDt[l * 8 + hh]);
;             sM[lp * 136 + s] = f2bf(v);
.LBB0_1949:
	s_or_b64 exec, exec, s[78:79]
	v_cvt_pk_bf16_f32 v18, v18, s0
	v_readlane_b32 s52, v255, 57
	ds_write_b16 v191, v18 offset:25664
	v_mov_b32_e32 v18, 0
	v_readlane_b32 s53, v255, 58
	s_and_saveexec_b64 s[78:79], s[52:53]
	s_cbranch_execz .LBB0_1951
	v_sub_f32_e32 v18, v23, v17
	v_mul_f32_e32 v18, 0x3fb8aa3b, v18
	v_exp_f32_e32 v18, v18
	s_nop 0
	v_mul_f32_e32 v18, v184, v18

; __device__ __forceinline__ bf f2bf(float f) { return (bf)(pk2(f, 0.f) & 0xFFFFu); }
; __device__ __forceinline__ void ssd_pass2(const Params& p, int layer, int task, char* sm) {
;     ...
;           for (int r = 0; r < 16; r++) {
;             const int lp = 32 * wr + 8 * (r >> 2) + 4 * h5 + (r & 3); const int l = 64 * lh + lp;
;             float v = 0.f;
;             if (s <= l) v = cb[j][r] * __expf(sAcs[l * 8 + hh] - as);
;             if (s == l) v += dsk * __builtin_amdgcn_rcpf(sDt[l * 8 + hh]);
;             sM[lp * 136 + s] = f2bf(v);
.LBB0_1953:
	s_or_b64 exec, exec, s[78:79]
	v_cvt_pk_bf16_f32 v18, v18, s0
	v_readlane_b32 s52, v255, 61
	ds_write_b16 v192, v18 offset:25664
	v_mov_b32_e32 v18, 0
	v_readlane_b32 s53, v255, 62
	s_and_saveexec_b64 s[78:79], s[52:53]
	s_cbranch_execz .LBB0_1955
	v_sub_f32_e32 v18, v24, v17
	v_mul_f32_e32 v18, 0x3fb8aa3b, v18
	v_exp_f32_e32 v18, v18
	s_nop 0
	v_mul_f32_e32 v18, v183, v18

; __device__ __forceinline__ bf f2bf(float f) { return (bf)(pk2(f, 0.f) & 0xFFFFu); }
; __device__ __forceinline__ void ssd_pass2(const Params& p, int layer, int task, char* sm) {
;     ...
;           for (int r = 0; r < 16; r++) {
;             const int lp = 32 * wr + 8 * (r >> 2) + 4 * h5 + (r & 3); const int l = 64 * lh + lp;
;             float v = 0.f;
;             if (s <= l) v = cb[j][r] * __expf(sAcs[l * 8 + hh] - as);
;             if (s == l) v += dsk * __builtin_amdgcn_rcpf(sDt[l * 8 + hh]);
;             sM[lp * 136 + s] = f2bf(v);
.LBB0_1957:
	s_or_b64 exec, exec, s[78:79]
	v_cvt_pk_bf16_f32 v18, v18, s0
	ds_write_b16 v193, v18 offset:25664
	v_mov_b32_e32 v18, 0
	s_and_saveexec_b64 s[78:79], s[92:93]
	s_cbranch_execz .LBB0_1959
	v_sub_f32_e32 v18, v25, v17
	v_mul_f32_e32 v18, 0x3fb8aa3b, v18
	v_exp_f32_e32 v18, v18
	s_nop 0
	v_mul_f32_e32 v18, v182, v18

; __device__ __forceinline__ bf f2bf(float f) { return (bf)(pk2(f, 0.f) & 0xFFFFu); }
; __device__ __forceinline__ void ssd_pass2(const Params& p, int layer, int task, char* sm) {
;     ...
;           for (int r = 0; r < 16; r++) {
;             const int lp = 32 * wr + 8 * (r >> 2) + 4 * h5 + (r & 3); const int l = 64 * lh + lp;
;             float v = 0.f;
;             if (s <= l) v = cb[j][r] * __expf(sAcs[l * 8 + hh] - as);
;             if (s == l) v += dsk * __builtin_amdgcn_rcpf(sDt[l * 8 + hh]);
;             sM[lp * 136 + s] = f2bf(v);
.LBB0_1961:
	s_or_b64 exec, exec, s[78:79]
	v_cvt_pk_bf16_f32 v18, v18, s0
	ds_write_b16 v194, v18 offset:25664
	v_mov_b32_e32 v18, 0
	s_and_saveexec_b64 s[78:79], s[96:97]
	s_cbranch_execz .LBB0_1963
	v_sub_f32_e32 v18, v26, v17
	v_mul_f32_e32 v18, 0x3fb8aa3b, v18
	v_exp_f32_e32 v18, v18
	s_nop 0
	v_mul_f32_e32 v18, v181, v18

; __device__ __forceinline__ bf f2bf(float f) { return (bf)(pk2(f, 0.f) & 0xFFFFu); }
; __device__ __forceinline__ void ssd_pass2(const Params& p, int layer, int task, char* sm) {
;     ...
;           for (int r = 0; r < 16; r++) {
;             const int lp = 32 * wr + 8 * (r >> 2) + 4 * h5 + (r & 3); const int l = 64 * lh + lp;
;             float v = 0.f;
;             if (s <= l) v = cb[j][r] * __expf(sAcs[l * 8 + hh] - as);
;             if (s == l) v += dsk * __builtin_amdgcn_rcpf(sDt[l * 8 + hh]);
;             sM[lp * 136 + s] = f2bf(v);
.LBB0_1965:
	s_or_b64 exec, exec, s[78:79]
	v_cvt_pk_bf16_f32 v18, v18, s0
	ds_write_b16 v195, v18 offset:25664
	v_mov_b32_e32 v18, 0
	s_and_saveexec_b64 s[78:79], s[8:9]
	s_cbranch_execz .LBB0_1967
	v_sub_f32_e32 v18, v27, v17
	v_mul_f32_e32 v18, 0x3fb8aa3b, v18
	v_exp_f32_e32 v18, v18
	s_nop 0
	v_mul_f32_e32 v18, v180, v18

; __device__ __forceinline__ bf f2bf(float f) { return (bf)(pk2(f, 0.f) & 0xFFFFu); }
; __device__ __forceinline__ void ssd_pass2(const Params& p, int layer, int task, char* sm) {
;     ...
;           for (int r = 0; r < 16; r++) {
;             const int lp = 32 * wr + 8 * (r >> 2) + 4 * h5 + (r & 3); const int l = 64 * lh + lp;
;             float v = 0.f;
;             if (s <= l) v = cb[j][r] * __expf(sAcs[l * 8 + hh] - as);
;             if (s == l) v += dsk * __builtin_amdgcn_rcpf(sDt[l * 8 + hh]);
;             sM[lp * 136 + s] = f2bf(v);
.LBB0_1969:
	s_or_b64 exec, exec, s[78:79]
	v_cvt_pk_bf16_f32 v18, v18, s0
	ds_write_b16 v196, v18 offset:25664
	v_mov_b32_e32 v18, 0
	s_and_saveexec_b64 s[78:79], s[10:11]
	s_cbranch_execz .LBB0_1971
	v_sub_f32_e32 v18, v28, v17
	v_mul_f32_e32 v18, 0x3fb8aa3b, v18
	v_exp_f32_e32 v18, v18
	s_nop 0
	v_mul_f32_e32 v18, v179, v18

; __device__ __forceinline__ bf f2bf(float f) { return (bf)(pk2(f, 0.f) & 0xFFFFu); }
; __device__ __forceinline__ void ssd_pass2(const Params& p, int layer, int task, char* sm) {
;     ...
;           for (int r = 0; r < 16; r++) {
;             const int lp = 32 * wr + 8 * (r >> 2) + 4 * h5 + (r & 3); const int l = 64 * lh + lp;
;             float v = 0.f;
;             if (s <= l) v = cb[j][r] * __expf(sAcs[l * 8 + hh] - as);
;             if (s == l) v += dsk * __builtin_amdgcn_rcpf(sDt[l * 8 + hh]);
;             sM[lp * 136 + s] = f2bf(v);
.LBB0_1973:
	s_or_b64 exec, exec, s[78:79]
	v_cvt_pk_bf16_f32 v18, v18, s0
	ds_write_b16 v197, v18 offset:25664
	v_mov_b32_e32 v18, 0
	s_and_saveexec_b64 s[78:79], s[14:15]
	s_cbranch_execz .LBB0_1975
	v_sub_f32_e32 v18, v29, v17
	v_mul_f32_e32 v18, 0x3fb8aa3b, v18
	v_exp_f32_e32 v18, v18
	s_nop 0
	v_mul_f32_e32 v18, v178, v18

; __device__ __forceinline__ bf f2bf(float f) { return (bf)(pk2(f, 0.f) & 0xFFFFu); }
; __device__ __forceinline__ void ssd_pass2(const Params& p, int layer, int task, char* sm) {
;     ...
;           for (int r = 0; r < 16; r++) {
;             const int lp = 32 * wr + 8 * (r >> 2) + 4 * h5 + (r & 3); const int l = 64 * lh + lp;
;             float v = 0.f;
;             if (s <= l) v = cb[j][r] * __expf(sAcs[l * 8 + hh] - as);
;             if (s == l) v += dsk * __builtin_amdgcn_rcpf(sDt[l * 8 + hh]);
;             sM[lp * 136 + s] = f2bf(v);
.LBB0_1977:
	s_or_b64 exec, exec, s[78:79]
	v_cvt_pk_bf16_f32 v18, v18, s0
	ds_write_b16 v213, v18 offset:25664
	v_mov_b32_e32 v18, 0
	s_and_saveexec_b64 s[78:79], s[18:19]
	s_cbranch_execz .LBB0_1979
	v_sub_f32_e32 v18, v30, v17
	v_mul_f32_e32 v18, 0x3fb8aa3b, v18
	v_exp_f32_e32 v18, v18
	s_nop 0
	v_mul_f32_e32 v18, v177, v18

; __device__ __forceinline__ bf f2bf(float f) { return (bf)(pk2(f, 0.f) & 0xFFFFu); }
; __device__ __forceinline__ void ssd_pass2(const Params& p, int layer, int task, char* sm) {
;     ...
;           for (int r = 0; r < 16; r++) {
;             const int lp = 32 * wr + 8 * (r >> 2) + 4 * h5 + (r & 3); const int l = 64 * lh + lp;
;             float v = 0.f;
;             if (s <= l) v = cb[j][r] * __expf(sAcs[l * 8 + hh] - as);
;             if (s == l) v += dsk * __builtin_amdgcn_rcpf(sDt[l * 8 + hh]);
;             sM[lp * 136 + s] = f2bf(v);
.LBB0_1981:
	s_or_b64 exec, exec, s[78:79]
	v_cvt_pk_bf16_f32 v18, v18, s0
	ds_write_b16 v214, v18 offset:25664
	v_mov_b32_e32 v18, 0
	s_and_saveexec_b64 s[78:79], s[24:25]
	s_cbranch_execz .LBB0_1983
	v_sub_f32_e32 v18, v31, v17
	v_mul_f32_e32 v18, 0x3fb8aa3b, v18
	v_exp_f32_e32 v18, v18
	s_nop 0
	v_mul_f32_e32 v18, v176, v18

; __device__ __forceinline__ bf f2bf(float f) { return (bf)(pk2(f, 0.f) & 0xFFFFu); }
; __device__ __forceinline__ void ssd_pass2(const Params& p, int layer, int task, char* sm) {
;     ...
;           for (int r = 0; r < 16; r++) {
;             const int lp = 32 * wr + 8 * (r >> 2) + 4 * h5 + (r & 3); const int l = 64 * lh + lp;
;             float v = 0.f;
;             if (s <= l) v = cb[j][r] * __expf(sAcs[l * 8 + hh] - as);
;             if (s == l) v += dsk * __builtin_amdgcn_rcpf(sDt[l * 8 + hh]);
;             sM[lp * 136 + s] = f2bf(v);
.LBB0_1985:
	s_or_b64 exec, exec, s[78:79]
	v_cvt_pk_bf16_f32 v18, v18, s0
	ds_write_b16 v215, v18 offset:25664
	v_mov_b32_e32 v18, 0
	s_and_saveexec_b64 s[78:79], s[28:29]
	s_cbranch_execz .LBB0_1987
	v_sub_f32_e32 v18, v32, v17
	v_mul_f32_e32 v18, 0x3fb8aa3b, v18
	v_exp_f32_e32 v18, v18
	s_nop 0
	v_mul_f32_e32 v18, v175, v18

; __device__ __forceinline__ bf f2bf(float f) { return (bf)(pk2(f, 0.f) & 0xFFFFu); }
; __device__ __forceinline__ void ssd_pass2(const Params& p, int layer, int task, char* sm) {
;     ...
;           for (int r = 0; r < 16; r++) {
;             const int lp = 32 * wr + 8 * (r >> 2) + 4 * h5 + (r & 3); const int l = 64 * lh + lp;
;             float v = 0.f;
;             if (s <= l) v = cb[j][r] * __expf(sAcs[l * 8 + hh] - as);
;             if (s == l) v += dsk * __builtin_amdgcn_rcpf(sDt[l * 8 + hh]);
;             sM[lp * 136 + s] = f2bf(v);
.LBB0_1989:
	s_or_b64 exec, exec, s[78:79]
	v_cvt_pk_bf16_f32 v18, v18, s0
	ds_write_b16 v216, v18 offset:25664
	v_mov_b32_e32 v18, 0
	s_and_saveexec_b64 s[78:79], s[34:35]
	s_cbranch_execz .LBB0_1991
	v_sub_f32_e32 v18, v33, v17
	v_mul_f32_e32 v18, 0x3fb8aa3b, v18
	v_exp_f32_e32 v18, v18
	s_nop 0
	v_mul_f32_e32 v18, v174, v18

; __device__ __forceinline__ bf f2bf(float f) { return (bf)(pk2(f, 0.f) & 0xFFFFu); }
; __device__ __forceinline__ void ssd_pass2(const Params& p, int layer, int task, char* sm) {
;     ...
;           for (int r = 0; r < 16; r++) {
;             const int lp = 32 * wr + 8 * (r >> 2) + 4 * h5 + (r & 3); const int l = 64 * lh + lp;
;             float v = 0.f;
;             if (s <= l) v = cb[j][r] * __expf(sAcs[l * 8 + hh] - as);
;             if (s == l) v += dsk * __builtin_amdgcn_rcpf(sDt[l * 8 + hh]);
;             sM[lp * 136 + s] = f2bf(v);
.LBB0_1993:
	s_or_b64 exec, exec, s[78:79]
	v_cvt_pk_bf16_f32 v18, v18, s0
	ds_write_b16 v217, v18 offset:25664
	v_mov_b32_e32 v18, 0
	s_and_saveexec_b64 s[78:79], s[38:39]
	s_cbranch_execz .LBB0_1995
	v_sub_f32_e32 v18, v34, v17
	v_mul_f32_e32 v18, 0x3fb8aa3b, v18
	v_exp_f32_e32 v18, v18
	s_nop 0
	v_mul_f32_e32 v18, v173, v18

; __device__ __forceinline__ bf f2bf(float f) { return (bf)(pk2(f, 0.f) & 0xFFFFu); }
; __device__ __forceinline__ void ssd_pass2(const Params& p, int layer, int task, char* sm) {
;     ...
;           for (int r = 0; r < 16; r++) {
;             const int lp = 32 * wr + 8 * (r >> 2) + 4 * h5 + (r & 3); const int l = 64 * lh + lp;
;             float v = 0.f;
;             if (s <= l) v = cb[j][r] * __expf(sAcs[l * 8 + hh] - as);
;             if (s == l) v += dsk * __builtin_amdgcn_rcpf(sDt[l * 8 + hh]);
;             sM[lp * 136 + s] = f2bf(v);
.LBB0_1997:
	s_or_b64 exec, exec, s[78:79]
	v_cvt_pk_bf16_f32 v18, v18, s0
	ds_write_b16 v218, v18 offset:25664
	v_mov_b32_e32 v18, 0
	s_and_saveexec_b64 s[78:79], s[42:43]
	s_cbranch_execz .LBB0_1999
	v_sub_f32_e32 v18, v35, v17
	v_mul_f32_e32 v18, 0x3fb8aa3b, v18
	v_exp_f32_e32 v18, v18
	s_nop 0
	v_mul_f32_e32 v18, v172, v18

; __device__ __forceinline__ bf f2bf(float f) { return (bf)(pk2(f, 0.f) & 0xFFFFu); }
; __device__ __forceinline__ void ssd_pass2(const Params& p, int layer, int task, char* sm) {
;     ...
;           for (int r = 0; r < 16; r++) {
;             const int lp = 32 * wr + 8 * (r >> 2) + 4 * h5 + (r & 3); const int l = 64 * lh + lp;
;             float v = 0.f;
;             if (s <= l) v = cb[j][r] * __expf(sAcs[l * 8 + hh] - as);
;             if (s == l) v += dsk * __builtin_amdgcn_rcpf(sDt[l * 8 + hh]);
;             sM[lp * 136 + s] = f2bf(v);
.LBB0_2001:
	s_or_b64 exec, exec, s[78:79]
	v_cvt_pk_bf16_f32 v18, v18, s0
	ds_write_b16 v219, v18 offset:25664
	v_mov_b32_e32 v18, 0
	s_and_saveexec_b64 s[78:79], s[46:47]
	s_cbranch_execz .LBB0_2003
	v_sub_f32_e32 v17, v36, v17
	v_mul_f32_e32 v17, 0x3fb8aa3b, v17
	v_exp_f32_e32 v17, v17
	s_nop 0
	v_mul_f32_e32 v18, v171, v17

; __device__ __forceinline__ bf f2bf(float f) { return (bf)(pk2(f, 0.f) & 0xFFFFu); }
; __device__ __forceinline__ void ssd_pass2(const Params& p, int layer, int task, char* sm) {
;     ...
;           for (int r = 0; r < 16; r++) {
;             const int lp = 32 * wr + 8 * (r >> 2) + 4 * h5 + (r & 3); const int l = 64 * lh + lp;
;             float v = 0.f;
;             if (s <= l) v = cb[j][r] * __expf(sAcs[l * 8 + hh] - as);
;             if (s == l) v += dsk * __builtin_amdgcn_rcpf(sDt[l * 8 + hh]);
;             sM[lp * 136 + s] = f2bf(v);
.LBB0_2211:
	s_or_b64 exec, exec, s[78:79]
	v_cvt_pk_bf16_f32 v18, v18, s0
	ds_write_b16 v195, v18 offset:25664
	v_mov_b32_e32 v18, 0
	s_and_saveexec_b64 s[78:79], s[2:3]
	s_cbranch_execz .LBB0_2213
	v_sub_f32_e32 v18, v27, v17
	v_mul_f32_e32 v18, 0x3fb8aa3b, v18
	v_exp_f32_e32 v18, v18
	s_nop 0
	v_mul_f32_e32 v18, v180, v18

; __device__ __forceinline__ bf f2bf(float f) { return (bf)(pk2(f, 0.f) & 0xFFFFu); }
; __device__ __forceinline__ void ssd_pass2(const Params& p, int layer, int task, char* sm) {
;     ...
;           for (int r = 0; r < 16; r++) {
;             const int lp = 32 * wr + 8 * (r >> 2) + 4 * h5 + (r & 3); const int l = 64 * lh + lp;
;             float v = 0.f;
;             if (s <= l) v = cb[j][r] * __expf(sAcs[l * 8 + hh] - as);
;             if (s == l) v += dsk * __builtin_amdgcn_rcpf(sDt[l * 8 + hh]);
;             sM[lp * 136 + s] = f2bf(v);
.LBB0_2239:
	s_or_b64 exec, exec, s[78:79]
	v_cvt_pk_bf16_f32 v18, v18, s0
	ds_write_b16 v217, v18 offset:25664
	v_mov_b32_e32 v18, 0
	s_and_saveexec_b64 s[78:79], s[38:39]
	s_cbranch_execz .LBB0_2241
	v_sub_f32_e32 v18, v34, v17
	v_mul_f32_e32 v18, 0x3fb8aa3b, v18
	v_exp_f32_e32 v18, v18
	s_nop 0
	v_mul_f32_e32 v18, v212, v18

; __device__ __forceinline__ bf f2bf(float f) { return (bf)(pk2(f, 0.f) & 0xFFFFu); }
; __device__ __forceinline__ void ssd_pass2(const Params& p, int layer, int task, char* sm) {
;     ...
;           for (int r = 0; r < 16; r++) {
;             const int lp = 32 * wr + 8 * (r >> 2) + 4 * h5 + (r & 3); const int l = 64 * lh + lp;
;             float v = 0.f;
;             if (s <= l) v = cb[j][r] * __expf(sAcs[l * 8 + hh] - as);
;             if (s == l) v += dsk * __builtin_amdgcn_rcpf(sDt[l * 8 + hh]);
;             sM[lp * 136 + s] = f2bf(v);
.LBB0_2243:
	s_or_b64 exec, exec, s[78:79]
	v_cvt_pk_bf16_f32 v18, v18, s0
	ds_write_b16 v218, v18 offset:25664
	v_mov_b32_e32 v18, 0
	s_and_saveexec_b64 s[78:79], s[42:43]
	s_cbranch_execz .LBB0_2245
	v_sub_f32_e32 v18, v35, v17
	v_mul_f32_e32 v18, 0x3fb8aa3b, v18
	v_exp_f32_e32 v18, v18
	s_nop 0
	v_mul_f32_e32 v18, v200, v18

; __device__ __forceinline__ bf f2bf(float f) { return (bf)(pk2(f, 0.f) & 0xFFFFu); }
; __device__ __forceinline__ void ssd_pass2(const Params& p, int layer, int task, char* sm) {
;     ...
;           for (int r = 0; r < 16; r++) {
;             const int lp = 32 * wr + 8 * (r >> 2) + 4 * h5 + (r & 3); const int l = 64 * lh + lp;
;             float v = 0.f;
;             if (s <= l) v = cb[j][r] * __expf(sAcs[l * 8 + hh] - as);
;             if (s == l) v += dsk * __builtin_amdgcn_rcpf(sDt[l * 8 + hh]);
;             sM[lp * 136 + s] = f2bf(v);
.LBB0_2247:
	s_or_b64 exec, exec, s[78:79]
	v_cvt_pk_bf16_f32 v18, v18, s0
	ds_write_b16 v219, v18 offset:25664
	v_mov_b32_e32 v18, 0
	s_and_saveexec_b64 s[78:79], s[46:47]
	s_cbranch_execz .LBB0_2249
	v_sub_f32_e32 v17, v36, v17
	v_mul_f32_e32 v17, 0x3fb8aa3b, v17
	v_exp_f32_e32 v17, v17
	s_nop 0
	v_mul_f32_e32 v18, v201, v17
